# compute-phase tail instructions (next-phase address / M0 / loop counter) moved in front of the last four MFMAs of the phase
# speedup vs baseline: 1.0184x; 1.0011x over previous
.LBB0_103:
	s_ashr_i32 s23, s22, 31
	s_lshl_b64 s[2:3], s[22:23], 19
	s_add_u32 s58, s90, s2
	s_addc_u32 s59, s77, s3
	s_and_b64 s[2:3], s[46:47], exec
	s_cselect_b32 s1, s59, s49
	s_cselect_b32 s23, s58, s48
	s_add_u32 s34, s34, 0x3e080
	s_addc_u32 s35, s35, 0
	s_add_u32 s51, s48, 0x100
	v_mov_b32_e32 v2, 0
	s_addc_u32 s52, s49, 0
	s_mov_b32 s53, -2
	s_add_u32 s2, s34, 0xfffc2080
	s_addc_u32 s3, s35, -1
	s_add_i32 s12, 0, 0x10000
	v_add_u32_e32 v110, s12, v179
	ds_read_b128 v[98:101], v110
	ds_read_b128 v[102:105], v110 offset:1024
	ds_read_b128 v[106:109], v110 offset:2048
	ds_read_b128 v[110:113], v110 offset:3072
	s_cmp_eq_u32 s53, 12
	s_cselect_b32 s49, s97, s3
	s_cselect_b32 s48, s96, s2
	s_cselect_b32 s3, s1, s52
	s_cselect_b32 s2, s23, s51
	v_lshl_add_u64 v[174:175], s[34:35], 0, v[170:171]
	s_add_i32 m0, s85, 0xc000
	ds_read_b128 v[114:117], v184
	ds_read_b128 v[118:121], v184 offset:1024
	ds_read_b128 v[122:125], v184 offset:2048
	ds_read_b128 v[126:129], v184 offset:3072
	ds_read_b128 v[186:189], v184 offset:4096
	ds_read_b128 v[190:193], v184 offset:5120
	ds_read_b128 v[194:197], v184 offset:6144
	ds_read_b128 v[198:201], v184 offset:7168
	global_load_lds_dwordx4 v[174:175], off
	v_lshl_add_u64 v[174:175], s[34:35], 0, v[172:173]
	s_add_i32 m0, s85, 0xe000
	s_nop 0
	global_load_lds_dwordx4 v[174:175], off
	s_waitcnt lgkmcnt(8)
	s_add_i32 s54, 0, 0x14000
	v_add_u32_e32 v174, s54, v179
	s_add_i32 s12, s12, s78
	ds_read_b128 v[226:229], v174
	ds_read_b128 v[230:233], v174 offset:1024
	ds_read_b128 v[234:237], v174 offset:2048
	ds_read_b128 v[242:245], v174 offset:3072
	s_barrier
	s_waitcnt lgkmcnt(0)
	v_mfma_f32_16x16x32_bf16 v[158:161], v[98:101], v[114:117], 0
	v_mfma_f32_16x16x32_bf16 v[154:157], v[106:109], v[114:117], 0
	v_mfma_f32_16x16x32_bf16 v[150:153], v[98:101], v[122:125], 0
	v_mfma_f32_16x16x32_bf16 v[146:149], v[106:109], v[122:125], 0
	v_mfma_f32_16x16x32_bf16 v[142:145], v[98:101], v[186:189], 0
	v_mfma_f32_16x16x32_bf16 v[138:141], v[106:109], v[186:189], 0
	v_mfma_f32_16x16x32_bf16 v[134:137], v[98:101], v[194:197], 0
	v_mfma_f32_16x16x32_bf16 v[130:133], v[106:109], v[194:197], 0
	v_mfma_f32_16x16x32_bf16 v[158:161], v[102:105], v[118:121], v[158:161]
	v_mfma_f32_16x16x32_bf16 v[154:157], v[110:113], v[118:121], v[154:157]
	v_mfma_f32_16x16x32_bf16 v[150:153], v[102:105], v[126:129], v[150:153]
	v_mfma_f32_16x16x32_bf16 v[146:149], v[110:113], v[126:129], v[146:149]
	v_mfma_f32_16x16x32_bf16 v[142:145], v[102:105], v[190:193], v[142:145]
	v_mfma_f32_16x16x32_bf16 v[138:141], v[110:113], v[190:193], v[138:141]
	v_mfma_f32_16x16x32_bf16 v[134:137], v[102:105], v[198:201], v[134:137]
	v_mfma_f32_16x16x32_bf16 v[130:133], v[110:113], v[198:201], v[130:133]
	v_mfma_f32_16x16x32_bf16 v[62:65], v[226:229], v[114:117], 0
	v_mfma_f32_16x16x32_bf16 v[58:61], v[234:237], v[114:117], 0
	v_mfma_f32_16x16x32_bf16 v[54:57], v[226:229], v[122:125], 0
	v_mfma_f32_16x16x32_bf16 v[50:53], v[234:237], v[122:125], 0
	v_mfma_f32_16x16x32_bf16 v[46:49], v[226:229], v[186:189], 0
	v_mfma_f32_16x16x32_bf16 v[42:45], v[234:237], v[186:189], 0
	v_mfma_f32_16x16x32_bf16 v[38:41], v[226:229], v[194:197], 0
	v_mfma_f32_16x16x32_bf16 v[34:37], v[234:237], v[194:197], 0
	v_mfma_f32_16x16x32_bf16 v[62:65], v[230:233], v[118:121], v[62:65]
	v_mfma_f32_16x16x32_bf16 v[58:61], v[242:245], v[118:121], v[58:61]
	v_mfma_f32_16x16x32_bf16 v[54:57], v[230:233], v[126:129], v[54:57]
	v_mfma_f32_16x16x32_bf16 v[50:53], v[242:245], v[126:129], v[50:53]
	s_mov_b32 m0, s85
	v_lshl_add_u64 v[248:249], s[48:49], 0, v[162:163]
	v_mfma_f32_16x16x32_bf16 v[46:49], v[230:233], v[190:193], v[46:49]
	v_mfma_f32_16x16x32_bf16 v[42:45], v[242:245], v[190:193], v[42:45]
	v_mfma_f32_16x16x32_bf16 v[38:41], v[230:233], v[198:201], v[38:41]
	v_mfma_f32_16x16x32_bf16 v[34:37], v[242:245], v[198:201], v[34:37]
	s_barrier
	ds_read_b128 v[114:117], v184 offset:16384
	ds_read_b128 v[118:121], v184 offset:17408
	ds_read_b128 v[122:125], v184 offset:18432
	ds_read_b128 v[126:129], v184 offset:19456
	ds_read_b128 v[186:189], v184 offset:20480
	ds_read_b128 v[190:193], v184 offset:21504
	ds_read_b128 v[194:197], v184 offset:22528
	ds_read_b128 v[198:201], v184 offset:23552
	global_load_lds_dwordx4 v[248:249], off
	v_lshl_add_u64 v[250:251], s[48:49], 0, v[164:165]
	s_mov_b32 m0, s82
	s_nop 0
	global_load_lds_dwordx4 v[250:251], off
	v_lshl_add_u64 v[174:175], s[2:3], 0, v[0:1]
	s_mov_b32 m0, s12
	v_lshl_add_u64 v[246:247], s[2:3], 0, v[166:167]
	global_load_lds_dwordx4 v[174:175], off
	s_add_i32 m0, s12, 0x2000
	s_nop 0
	global_load_lds_dwordx4 v[246:247], off
	s_add_u32 s12, s2, 0x40000
	s_addc_u32 s13, s3, 0
	s_add_i32 s54, s54, s78
	v_lshl_add_u64 v[174:175], s[12:13], 0, v[0:1]
	s_mov_b32 m0, s54
	s_nop 0
	global_load_lds_dwordx4 v[174:175], off
	v_lshl_add_u64 v[174:175], s[12:13], 0, v[166:167]
	s_add_i32 m0, s54, 0x2000
	s_nop 0
	global_load_lds_dwordx4 v[174:175], off
	s_waitcnt vmcnt(6)
	s_barrier
	s_waitcnt lgkmcnt(0)
	v_mfma_f32_16x16x32_bf16 v[94:97], v[98:101], v[114:117], 0
	v_mfma_f32_16x16x32_bf16 v[90:93], v[106:109], v[114:117], 0
	v_mfma_f32_16x16x32_bf16 v[86:89], v[98:101], v[122:125], 0
	v_mfma_f32_16x16x32_bf16 v[82:85], v[106:109], v[122:125], 0
	v_mfma_f32_16x16x32_bf16 v[78:81], v[98:101], v[186:189], 0
	v_mfma_f32_16x16x32_bf16 v[74:77], v[106:109], v[186:189], 0
	v_mfma_f32_16x16x32_bf16 v[70:73], v[98:101], v[194:197], 0
	v_mfma_f32_16x16x32_bf16 v[66:69], v[106:109], v[194:197], 0
	v_mfma_f32_16x16x32_bf16 v[94:97], v[102:105], v[118:121], v[94:97]
	v_mfma_f32_16x16x32_bf16 v[90:93], v[110:113], v[118:121], v[90:93]
	v_mfma_f32_16x16x32_bf16 v[86:89], v[102:105], v[126:129], v[86:89]
	v_mfma_f32_16x16x32_bf16 v[82:85], v[110:113], v[126:129], v[82:85]
	v_mfma_f32_16x16x32_bf16 v[78:81], v[102:105], v[190:193], v[78:81]
	v_mfma_f32_16x16x32_bf16 v[74:77], v[110:113], v[190:193], v[74:77]
	v_mfma_f32_16x16x32_bf16 v[70:73], v[102:105], v[198:201], v[70:73]
	v_mfma_f32_16x16x32_bf16 v[66:69], v[110:113], v[198:201], v[66:69]
	v_mfma_f32_16x16x32_bf16 v[30:33], v[226:229], v[114:117], 0
	v_mfma_f32_16x16x32_bf16 v[26:29], v[234:237], v[114:117], 0
	v_mfma_f32_16x16x32_bf16 v[22:25], v[226:229], v[122:125], 0
	v_mfma_f32_16x16x32_bf16 v[18:21], v[234:237], v[122:125], 0
	v_mfma_f32_16x16x32_bf16 v[14:17], v[226:229], v[186:189], 0
	v_mfma_f32_16x16x32_bf16 v[10:13], v[234:237], v[186:189], 0
	v_mfma_f32_16x16x32_bf16 v[6:9], v[226:229], v[194:197], 0
	v_mfma_f32_16x16x32_bf16 v[2:5], v[234:237], v[194:197], 0
	v_mfma_f32_16x16x32_bf16 v[30:33], v[230:233], v[118:121], v[30:33]
	v_mfma_f32_16x16x32_bf16 v[26:29], v[242:245], v[118:121], v[26:29]
	v_mfma_f32_16x16x32_bf16 v[22:25], v[230:233], v[126:129], v[22:25]
	v_mfma_f32_16x16x32_bf16 v[18:21], v[242:245], v[126:129], v[18:21]
	s_add_i32 s54, 0, 0x18000
	v_add_u32_e32 v110, s54, v179
	v_mfma_f32_16x16x32_bf16 v[14:17], v[230:233], v[190:193], v[14:17]
	v_mfma_f32_16x16x32_bf16 v[10:13], v[242:245], v[190:193], v[10:13]
	v_mfma_f32_16x16x32_bf16 v[6:9], v[230:233], v[198:201], v[6:9]
	v_mfma_f32_16x16x32_bf16 v[2:5], v[242:245], v[198:201], v[2:5]
	s_barrier
	ds_read_b128 v[98:101], v110
	ds_read_b128 v[102:105], v110 offset:1024
	ds_read_b128 v[106:109], v110 offset:2048
	ds_read_b128 v[110:113], v110 offset:3072
	s_add_u32 s12, s48, 0x3e000
	s_addc_u32 s13, s49, 0
	s_mov_b32 m0, s89
	v_lshl_add_u64 v[226:227], s[12:13], 0, v[162:163]
	ds_read_b128 v[114:117], v184 offset:32768
	ds_read_b128 v[118:121], v184 offset:33792
	ds_read_b128 v[122:125], v184 offset:34816
	ds_read_b128 v[126:129], v184 offset:35840
	ds_read_b128 v[186:189], v184 offset:36864
	ds_read_b128 v[190:193], v184 offset:37888
	ds_read_b128 v[194:197], v184 offset:38912
	ds_read_b128 v[198:201], v184 offset:39936
	global_load_lds_dwordx4 v[226:227], off
	v_lshl_add_u64 v[226:227], s[12:13], 0, v[164:165]
	s_mov_b32 m0, s91
	s_nop 0
	global_load_lds_dwordx4 v[226:227], off
	s_waitcnt lgkmcnt(8)
	s_add_i32 s12, 0, 0x1c000
	s_add_i32 s13, s54, s78
	v_add_u32_e32 v242, s12, v179
	ds_read_b128 v[226:229], v242
	ds_read_b128 v[230:233], v242 offset:1024
	ds_read_b128 v[234:237], v242 offset:2048
	ds_read_b128 v[242:245], v242 offset:3072
	s_barrier
	s_waitcnt lgkmcnt(0)
	s_nop 0
	v_mfma_f32_16x16x32_bf16 v[158:161], v[98:101], v[114:117], v[158:161]
	v_mfma_f32_16x16x32_bf16 v[154:157], v[106:109], v[114:117], v[154:157]
	v_mfma_f32_16x16x32_bf16 v[150:153], v[98:101], v[122:125], v[150:153]
	v_mfma_f32_16x16x32_bf16 v[146:149], v[106:109], v[122:125], v[146:149]
	v_mfma_f32_16x16x32_bf16 v[142:145], v[98:101], v[186:189], v[142:145]
	v_mfma_f32_16x16x32_bf16 v[138:141], v[106:109], v[186:189], v[138:141]
	v_mfma_f32_16x16x32_bf16 v[134:137], v[98:101], v[194:197], v[134:137]
	v_mfma_f32_16x16x32_bf16 v[130:133], v[106:109], v[194:197], v[130:133]
	v_mfma_f32_16x16x32_bf16 v[158:161], v[102:105], v[118:121], v[158:161]
	v_mfma_f32_16x16x32_bf16 v[154:157], v[110:113], v[118:121], v[154:157]
	v_mfma_f32_16x16x32_bf16 v[150:153], v[102:105], v[126:129], v[150:153]
	v_mfma_f32_16x16x32_bf16 v[146:149], v[110:113], v[126:129], v[146:149]
	v_mfma_f32_16x16x32_bf16 v[142:145], v[102:105], v[190:193], v[142:145]
	v_mfma_f32_16x16x32_bf16 v[138:141], v[110:113], v[190:193], v[138:141]
	v_mfma_f32_16x16x32_bf16 v[134:137], v[102:105], v[198:201], v[134:137]
	v_mfma_f32_16x16x32_bf16 v[130:133], v[110:113], v[198:201], v[130:133]
	v_mfma_f32_16x16x32_bf16 v[62:65], v[226:229], v[114:117], v[62:65]
	v_mfma_f32_16x16x32_bf16 v[58:61], v[234:237], v[114:117], v[58:61]
	v_mfma_f32_16x16x32_bf16 v[54:57], v[226:229], v[122:125], v[54:57]
	v_mfma_f32_16x16x32_bf16 v[50:53], v[234:237], v[122:125], v[50:53]
	v_mfma_f32_16x16x32_bf16 v[46:49], v[226:229], v[186:189], v[46:49]
	v_mfma_f32_16x16x32_bf16 v[42:45], v[234:237], v[186:189], v[42:45]
	v_mfma_f32_16x16x32_bf16 v[38:41], v[226:229], v[194:197], v[38:41]
	v_mfma_f32_16x16x32_bf16 v[34:37], v[234:237], v[194:197], v[34:37]
	v_mfma_f32_16x16x32_bf16 v[62:65], v[230:233], v[118:121], v[62:65]
	v_mfma_f32_16x16x32_bf16 v[58:61], v[242:245], v[118:121], v[58:61]
	v_mfma_f32_16x16x32_bf16 v[54:57], v[230:233], v[126:129], v[54:57]
	v_mfma_f32_16x16x32_bf16 v[50:53], v[242:245], v[126:129], v[50:53]
	s_mov_b32 m0, s79
	v_lshl_add_u64 v[174:175], v[248:249], 0, s[20:21]
	v_mfma_f32_16x16x32_bf16 v[46:49], v[230:233], v[190:193], v[46:49]
	v_mfma_f32_16x16x32_bf16 v[42:45], v[242:245], v[190:193], v[42:45]
	v_mfma_f32_16x16x32_bf16 v[38:41], v[230:233], v[198:201], v[38:41]
	v_mfma_f32_16x16x32_bf16 v[34:37], v[242:245], v[198:201], v[34:37]
	s_barrier
	ds_read_b128 v[114:117], v184 offset:49152
	ds_read_b128 v[118:121], v184 offset:50176
	ds_read_b128 v[122:125], v184 offset:51200
	ds_read_b128 v[126:129], v184 offset:52224
	ds_read_b128 v[186:189], v184 offset:53248
	ds_read_b128 v[190:193], v184 offset:54272
	ds_read_b128 v[194:197], v184 offset:55296
	ds_read_b128 v[198:201], v184 offset:56320
	global_load_lds_dwordx4 v[174:175], off
	v_lshl_add_u64 v[174:175], v[250:251], 0, s[20:21]
	s_mov_b32 m0, s87
	s_nop 0
	global_load_lds_dwordx4 v[174:175], off
	v_lshl_add_u64 v[174:175], s[2:3], 0, v[0:1]
	v_lshl_add_u64 v[174:175], v[174:175], 0, s[20:21]
	s_mov_b32 m0, s13
	s_nop 0
	global_load_lds_dwordx4 v[174:175], off
	v_lshl_add_u64 v[174:175], v[246:247], 0, s[20:21]
	s_add_i32 m0, s13, 0x2000
	s_nop 0
	global_load_lds_dwordx4 v[174:175], off
	s_add_u32 s2, s2, 0x40080
	s_addc_u32 s3, s3, 0
	s_add_i32 s12, s12, s78
	v_lshl_add_u64 v[174:175], s[2:3], 0, v[0:1]
	s_mov_b32 m0, s12
	s_nop 0
	global_load_lds_dwordx4 v[174:175], off
	v_lshl_add_u64 v[174:175], s[2:3], 0, v[166:167]
	s_add_i32 m0, s12, 0x2000
	s_nop 0
	global_load_lds_dwordx4 v[174:175], off
	s_waitcnt vmcnt(6)
	s_barrier
	s_waitcnt lgkmcnt(0)
	s_nop 0
	v_mfma_f32_16x16x32_bf16 v[94:97], v[98:101], v[114:117], v[94:97]
	v_mfma_f32_16x16x32_bf16 v[90:93], v[106:109], v[114:117], v[90:93]
	v_mfma_f32_16x16x32_bf16 v[86:89], v[98:101], v[122:125], v[86:89]
	v_mfma_f32_16x16x32_bf16 v[82:85], v[106:109], v[122:125], v[82:85]
	v_mfma_f32_16x16x32_bf16 v[78:81], v[98:101], v[186:189], v[78:81]
	v_mfma_f32_16x16x32_bf16 v[74:77], v[106:109], v[186:189], v[74:77]
	v_mfma_f32_16x16x32_bf16 v[70:73], v[98:101], v[194:197], v[70:73]
	v_mfma_f32_16x16x32_bf16 v[66:69], v[106:109], v[194:197], v[66:69]
	v_mfma_f32_16x16x32_bf16 v[94:97], v[102:105], v[118:121], v[94:97]
	v_mfma_f32_16x16x32_bf16 v[90:93], v[110:113], v[118:121], v[90:93]
	v_mfma_f32_16x16x32_bf16 v[86:89], v[102:105], v[126:129], v[86:89]
	v_mfma_f32_16x16x32_bf16 v[82:85], v[110:113], v[126:129], v[82:85]
	v_mfma_f32_16x16x32_bf16 v[78:81], v[102:105], v[190:193], v[78:81]
	v_mfma_f32_16x16x32_bf16 v[74:77], v[110:113], v[190:193], v[74:77]
	v_mfma_f32_16x16x32_bf16 v[70:73], v[102:105], v[198:201], v[70:73]
	v_mfma_f32_16x16x32_bf16 v[66:69], v[110:113], v[198:201], v[66:69]
	v_mfma_f32_16x16x32_bf16 v[30:33], v[226:229], v[114:117], v[30:33]
	v_mfma_f32_16x16x32_bf16 v[26:29], v[234:237], v[114:117], v[26:29]
	v_mfma_f32_16x16x32_bf16 v[22:25], v[226:229], v[122:125], v[22:25]
	v_mfma_f32_16x16x32_bf16 v[18:21], v[234:237], v[122:125], v[18:21]
	v_mfma_f32_16x16x32_bf16 v[14:17], v[226:229], v[186:189], v[14:17]
	v_mfma_f32_16x16x32_bf16 v[10:13], v[234:237], v[186:189], v[10:13]
	v_mfma_f32_16x16x32_bf16 v[6:9], v[226:229], v[194:197], v[6:9]
	v_mfma_f32_16x16x32_bf16 v[2:5], v[234:237], v[194:197], v[2:5]
	v_mfma_f32_16x16x32_bf16 v[30:33], v[230:233], v[118:121], v[30:33]
	v_mfma_f32_16x16x32_bf16 v[26:29], v[242:245], v[118:121], v[26:29]
	v_mfma_f32_16x16x32_bf16 v[22:25], v[230:233], v[126:129], v[22:25]
	v_mfma_f32_16x16x32_bf16 v[18:21], v[242:245], v[126:129], v[18:21]
	s_add_i32 s53, s53, 2
	s_add_u32 s34, s34, 0x100
	s_addc_u32 s35, s35, 0
	s_add_u32 s51, s51, 0x100
	s_addc_u32 s52, s52, 0
	s_cmp_gt_u32 s53, 13
	v_mfma_f32_16x16x32_bf16 v[14:17], v[230:233], v[190:193], v[14:17]
	v_mfma_f32_16x16x32_bf16 v[10:13], v[242:245], v[190:193], v[10:13]
	v_mfma_f32_16x16x32_bf16 v[6:9], v[230:233], v[198:201], v[6:9]
	v_mfma_f32_16x16x32_bf16 v[2:5], v[242:245], v[198:201], v[2:5]
	s_barrier
	s_cbranch_scc1 .Lpeel_x_0
.LBB0_104:
	s_add_u32 s2, s34, 0xfffc2080
	s_addc_u32 s3, s35, -1
	s_add_i32 s12, 0, 0x10000
	v_add_u32_e32 v110, s12, v179
	ds_read_b128 v[98:101], v110
	ds_read_b128 v[102:105], v110 offset:1024
	ds_read_b128 v[106:109], v110 offset:2048
	ds_read_b128 v[110:113], v110 offset:3072
	s_cmp_eq_u32 s53, 12
	s_cselect_b32 s49, s97, s3
	s_cselect_b32 s48, s96, s2
	s_cselect_b32 s3, s1, s52
	s_cselect_b32 s2, s23, s51
	v_lshl_add_u64 v[174:175], s[34:35], 0, v[170:171]
	s_add_i32 m0, s85, 0xc000
	ds_read_b128 v[114:117], v184
	ds_read_b128 v[118:121], v184 offset:1024
	ds_read_b128 v[122:125], v184 offset:2048
	ds_read_b128 v[126:129], v184 offset:3072
	ds_read_b128 v[186:189], v184 offset:4096
	ds_read_b128 v[190:193], v184 offset:5120
	ds_read_b128 v[194:197], v184 offset:6144
	ds_read_b128 v[198:201], v184 offset:7168
	global_load_lds_dwordx4 v[174:175], off
	v_lshl_add_u64 v[174:175], s[34:35], 0, v[172:173]
	s_add_i32 m0, s85, 0xe000
	s_nop 0
	global_load_lds_dwordx4 v[174:175], off
	s_waitcnt lgkmcnt(8)
	s_add_i32 s54, 0, 0x14000
	v_add_u32_e32 v174, s54, v179
	s_add_i32 s12, s12, s78
	ds_read_b128 v[226:229], v174
	ds_read_b128 v[230:233], v174 offset:1024
	ds_read_b128 v[234:237], v174 offset:2048
	ds_read_b128 v[242:245], v174 offset:3072
	s_barrier
	s_waitcnt lgkmcnt(0)
	s_nop 0
	v_mfma_f32_16x16x32_bf16 v[158:161], v[98:101], v[114:117], v[158:161]
	v_mfma_f32_16x16x32_bf16 v[154:157], v[106:109], v[114:117], v[154:157]
	v_mfma_f32_16x16x32_bf16 v[150:153], v[98:101], v[122:125], v[150:153]
	v_mfma_f32_16x16x32_bf16 v[146:149], v[106:109], v[122:125], v[146:149]
	v_mfma_f32_16x16x32_bf16 v[142:145], v[98:101], v[186:189], v[142:145]
	v_mfma_f32_16x16x32_bf16 v[138:141], v[106:109], v[186:189], v[138:141]
	v_mfma_f32_16x16x32_bf16 v[134:137], v[98:101], v[194:197], v[134:137]
	v_mfma_f32_16x16x32_bf16 v[130:133], v[106:109], v[194:197], v[130:133]
	v_mfma_f32_16x16x32_bf16 v[158:161], v[102:105], v[118:121], v[158:161]
	v_mfma_f32_16x16x32_bf16 v[154:157], v[110:113], v[118:121], v[154:157]
	v_mfma_f32_16x16x32_bf16 v[150:153], v[102:105], v[126:129], v[150:153]
	v_mfma_f32_16x16x32_bf16 v[146:149], v[110:113], v[126:129], v[146:149]
	v_mfma_f32_16x16x32_bf16 v[142:145], v[102:105], v[190:193], v[142:145]
	v_mfma_f32_16x16x32_bf16 v[138:141], v[110:113], v[190:193], v[138:141]
	v_mfma_f32_16x16x32_bf16 v[134:137], v[102:105], v[198:201], v[134:137]
	v_mfma_f32_16x16x32_bf16 v[130:133], v[110:113], v[198:201], v[130:133]
	v_mfma_f32_16x16x32_bf16 v[62:65], v[226:229], v[114:117], v[62:65]
	v_mfma_f32_16x16x32_bf16 v[58:61], v[234:237], v[114:117], v[58:61]
	v_mfma_f32_16x16x32_bf16 v[54:57], v[226:229], v[122:125], v[54:57]
	v_mfma_f32_16x16x32_bf16 v[50:53], v[234:237], v[122:125], v[50:53]
	v_mfma_f32_16x16x32_bf16 v[46:49], v[226:229], v[186:189], v[46:49]
	v_mfma_f32_16x16x32_bf16 v[42:45], v[234:237], v[186:189], v[42:45]
	v_mfma_f32_16x16x32_bf16 v[38:41], v[226:229], v[194:197], v[38:41]
	v_mfma_f32_16x16x32_bf16 v[34:37], v[234:237], v[194:197], v[34:37]
	v_mfma_f32_16x16x32_bf16 v[62:65], v[230:233], v[118:121], v[62:65]
	v_mfma_f32_16x16x32_bf16 v[58:61], v[242:245], v[118:121], v[58:61]
	v_mfma_f32_16x16x32_bf16 v[54:57], v[230:233], v[126:129], v[54:57]
	v_mfma_f32_16x16x32_bf16 v[50:53], v[242:245], v[126:129], v[50:53]
	s_mov_b32 m0, s85
	v_lshl_add_u64 v[248:249], s[48:49], 0, v[162:163]
	v_mfma_f32_16x16x32_bf16 v[46:49], v[230:233], v[190:193], v[46:49]
	v_mfma_f32_16x16x32_bf16 v[42:45], v[242:245], v[190:193], v[42:45]
	v_mfma_f32_16x16x32_bf16 v[38:41], v[230:233], v[198:201], v[38:41]
	v_mfma_f32_16x16x32_bf16 v[34:37], v[242:245], v[198:201], v[34:37]
	s_barrier
	ds_read_b128 v[114:117], v184 offset:16384
	ds_read_b128 v[118:121], v184 offset:17408
	ds_read_b128 v[122:125], v184 offset:18432
	ds_read_b128 v[126:129], v184 offset:19456
	ds_read_b128 v[186:189], v184 offset:20480
	ds_read_b128 v[190:193], v184 offset:21504
	ds_read_b128 v[194:197], v184 offset:22528
	ds_read_b128 v[198:201], v184 offset:23552
	global_load_lds_dwordx4 v[248:249], off
	v_lshl_add_u64 v[250:251], s[48:49], 0, v[164:165]
	s_mov_b32 m0, s82
	s_nop 0
	global_load_lds_dwordx4 v[250:251], off
	v_lshl_add_u64 v[174:175], s[2:3], 0, v[0:1]
	s_mov_b32 m0, s12
	v_lshl_add_u64 v[246:247], s[2:3], 0, v[166:167]
	global_load_lds_dwordx4 v[174:175], off
	s_add_i32 m0, s12, 0x2000
	s_nop 0
	global_load_lds_dwordx4 v[246:247], off
	s_add_u32 s12, s2, 0x40000
	s_addc_u32 s13, s3, 0
	s_add_i32 s54, s54, s78
	v_lshl_add_u64 v[174:175], s[12:13], 0, v[0:1]
	s_mov_b32 m0, s54
	s_nop 0
	global_load_lds_dwordx4 v[174:175], off
	v_lshl_add_u64 v[174:175], s[12:13], 0, v[166:167]
	s_add_i32 m0, s54, 0x2000
	s_nop 0
	global_load_lds_dwordx4 v[174:175], off
	s_waitcnt vmcnt(6)
	s_barrier
	s_waitcnt lgkmcnt(0)
	v_mfma_f32_16x16x32_bf16 v[94:97], v[98:101], v[114:117], v[94:97]
	v_mfma_f32_16x16x32_bf16 v[90:93], v[106:109], v[114:117], v[90:93]
	v_mfma_f32_16x16x32_bf16 v[86:89], v[98:101], v[122:125], v[86:89]
	v_mfma_f32_16x16x32_bf16 v[82:85], v[106:109], v[122:125], v[82:85]
	v_mfma_f32_16x16x32_bf16 v[78:81], v[98:101], v[186:189], v[78:81]
	v_mfma_f32_16x16x32_bf16 v[74:77], v[106:109], v[186:189], v[74:77]
	v_mfma_f32_16x16x32_bf16 v[70:73], v[98:101], v[194:197], v[70:73]
	v_mfma_f32_16x16x32_bf16 v[66:69], v[106:109], v[194:197], v[66:69]
	v_mfma_f32_16x16x32_bf16 v[94:97], v[102:105], v[118:121], v[94:97]
	v_mfma_f32_16x16x32_bf16 v[90:93], v[110:113], v[118:121], v[90:93]
	v_mfma_f32_16x16x32_bf16 v[86:89], v[102:105], v[126:129], v[86:89]
	v_mfma_f32_16x16x32_bf16 v[82:85], v[110:113], v[126:129], v[82:85]
	v_mfma_f32_16x16x32_bf16 v[78:81], v[102:105], v[190:193], v[78:81]
	v_mfma_f32_16x16x32_bf16 v[74:77], v[110:113], v[190:193], v[74:77]
	v_mfma_f32_16x16x32_bf16 v[70:73], v[102:105], v[198:201], v[70:73]
	v_mfma_f32_16x16x32_bf16 v[66:69], v[110:113], v[198:201], v[66:69]
	v_mfma_f32_16x16x32_bf16 v[30:33], v[226:229], v[114:117], v[30:33]
	v_mfma_f32_16x16x32_bf16 v[26:29], v[234:237], v[114:117], v[26:29]
	v_mfma_f32_16x16x32_bf16 v[22:25], v[226:229], v[122:125], v[22:25]
	v_mfma_f32_16x16x32_bf16 v[18:21], v[234:237], v[122:125], v[18:21]
	v_mfma_f32_16x16x32_bf16 v[14:17], v[226:229], v[186:189], v[14:17]
	v_mfma_f32_16x16x32_bf16 v[10:13], v[234:237], v[186:189], v[10:13]
	v_mfma_f32_16x16x32_bf16 v[6:9], v[226:229], v[194:197], v[6:9]
	v_mfma_f32_16x16x32_bf16 v[2:5], v[234:237], v[194:197], v[2:5]
	v_mfma_f32_16x16x32_bf16 v[30:33], v[230:233], v[118:121], v[30:33]
	v_mfma_f32_16x16x32_bf16 v[26:29], v[242:245], v[118:121], v[26:29]
	v_mfma_f32_16x16x32_bf16 v[22:25], v[230:233], v[126:129], v[22:25]
	v_mfma_f32_16x16x32_bf16 v[18:21], v[242:245], v[126:129], v[18:21]
	s_add_i32 s54, 0, 0x18000
	v_add_u32_e32 v110, s54, v179
	v_mfma_f32_16x16x32_bf16 v[14:17], v[230:233], v[190:193], v[14:17]
	v_mfma_f32_16x16x32_bf16 v[10:13], v[242:245], v[190:193], v[10:13]
	v_mfma_f32_16x16x32_bf16 v[6:9], v[230:233], v[198:201], v[6:9]
	v_mfma_f32_16x16x32_bf16 v[2:5], v[242:245], v[198:201], v[2:5]
	s_barrier
	ds_read_b128 v[98:101], v110
	ds_read_b128 v[102:105], v110 offset:1024
	ds_read_b128 v[106:109], v110 offset:2048
	ds_read_b128 v[110:113], v110 offset:3072
	s_add_u32 s12, s48, 0x3e000
	s_addc_u32 s13, s49, 0
	s_mov_b32 m0, s89
	v_lshl_add_u64 v[226:227], s[12:13], 0, v[162:163]
	ds_read_b128 v[114:117], v184 offset:32768
	ds_read_b128 v[118:121], v184 offset:33792
	ds_read_b128 v[122:125], v184 offset:34816
	ds_read_b128 v[126:129], v184 offset:35840
	ds_read_b128 v[186:189], v184 offset:36864
	ds_read_b128 v[190:193], v184 offset:37888
	ds_read_b128 v[194:197], v184 offset:38912
	ds_read_b128 v[198:201], v184 offset:39936
	global_load_lds_dwordx4 v[226:227], off
	v_lshl_add_u64 v[226:227], s[12:13], 0, v[164:165]
	s_mov_b32 m0, s91
	s_nop 0
	global_load_lds_dwordx4 v[226:227], off
	s_waitcnt lgkmcnt(8)
	s_add_i32 s12, 0, 0x1c000
	s_add_i32 s13, s54, s78
	v_add_u32_e32 v242, s12, v179
	ds_read_b128 v[226:229], v242
	ds_read_b128 v[230:233], v242 offset:1024
	ds_read_b128 v[234:237], v242 offset:2048
	ds_read_b128 v[242:245], v242 offset:3072
	s_barrier
	s_waitcnt lgkmcnt(0)
	s_nop 0
	v_mfma_f32_16x16x32_bf16 v[158:161], v[98:101], v[114:117], v[158:161]
	v_mfma_f32_16x16x32_bf16 v[154:157], v[106:109], v[114:117], v[154:157]
	v_mfma_f32_16x16x32_bf16 v[150:153], v[98:101], v[122:125], v[150:153]
	v_mfma_f32_16x16x32_bf16 v[146:149], v[106:109], v[122:125], v[146:149]
	v_mfma_f32_16x16x32_bf16 v[142:145], v[98:101], v[186:189], v[142:145]
	v_mfma_f32_16x16x32_bf16 v[138:141], v[106:109], v[186:189], v[138:141]
	v_mfma_f32_16x16x32_bf16 v[134:137], v[98:101], v[194:197], v[134:137]
	v_mfma_f32_16x16x32_bf16 v[130:133], v[106:109], v[194:197], v[130:133]
	v_mfma_f32_16x16x32_bf16 v[158:161], v[102:105], v[118:121], v[158:161]
	v_mfma_f32_16x16x32_bf16 v[154:157], v[110:113], v[118:121], v[154:157]
	v_mfma_f32_16x16x32_bf16 v[150:153], v[102:105], v[126:129], v[150:153]
	v_mfma_f32_16x16x32_bf16 v[146:149], v[110:113], v[126:129], v[146:149]
	v_mfma_f32_16x16x32_bf16 v[142:145], v[102:105], v[190:193], v[142:145]
	v_mfma_f32_16x16x32_bf16 v[138:141], v[110:113], v[190:193], v[138:141]
	v_mfma_f32_16x16x32_bf16 v[134:137], v[102:105], v[198:201], v[134:137]
	v_mfma_f32_16x16x32_bf16 v[130:133], v[110:113], v[198:201], v[130:133]
	v_mfma_f32_16x16x32_bf16 v[62:65], v[226:229], v[114:117], v[62:65]
	v_mfma_f32_16x16x32_bf16 v[58:61], v[234:237], v[114:117], v[58:61]
	v_mfma_f32_16x16x32_bf16 v[54:57], v[226:229], v[122:125], v[54:57]
	v_mfma_f32_16x16x32_bf16 v[50:53], v[234:237], v[122:125], v[50:53]
	v_mfma_f32_16x16x32_bf16 v[46:49], v[226:229], v[186:189], v[46:49]
	v_mfma_f32_16x16x32_bf16 v[42:45], v[234:237], v[186:189], v[42:45]
	v_mfma_f32_16x16x32_bf16 v[38:41], v[226:229], v[194:197], v[38:41]
	v_mfma_f32_16x16x32_bf16 v[34:37], v[234:237], v[194:197], v[34:37]
	v_mfma_f32_16x16x32_bf16 v[62:65], v[230:233], v[118:121], v[62:65]
	v_mfma_f32_16x16x32_bf16 v[58:61], v[242:245], v[118:121], v[58:61]
	v_mfma_f32_16x16x32_bf16 v[54:57], v[230:233], v[126:129], v[54:57]
	v_mfma_f32_16x16x32_bf16 v[50:53], v[242:245], v[126:129], v[50:53]
	s_mov_b32 m0, s79
	v_lshl_add_u64 v[174:175], v[248:249], 0, s[20:21]
	v_mfma_f32_16x16x32_bf16 v[46:49], v[230:233], v[190:193], v[46:49]
	v_mfma_f32_16x16x32_bf16 v[42:45], v[242:245], v[190:193], v[42:45]
	v_mfma_f32_16x16x32_bf16 v[38:41], v[230:233], v[198:201], v[38:41]
	v_mfma_f32_16x16x32_bf16 v[34:37], v[242:245], v[198:201], v[34:37]
	s_barrier
	ds_read_b128 v[114:117], v184 offset:49152
	ds_read_b128 v[118:121], v184 offset:50176
	ds_read_b128 v[122:125], v184 offset:51200
	ds_read_b128 v[126:129], v184 offset:52224
	ds_read_b128 v[186:189], v184 offset:53248
	ds_read_b128 v[190:193], v184 offset:54272
	ds_read_b128 v[194:197], v184 offset:55296
	ds_read_b128 v[198:201], v184 offset:56320
	global_load_lds_dwordx4 v[174:175], off
	v_lshl_add_u64 v[174:175], v[250:251], 0, s[20:21]
	s_mov_b32 m0, s87
	s_nop 0
	global_load_lds_dwordx4 v[174:175], off
	v_lshl_add_u64 v[174:175], s[2:3], 0, v[0:1]
	v_lshl_add_u64 v[174:175], v[174:175], 0, s[20:21]
	s_mov_b32 m0, s13
	s_nop 0
	global_load_lds_dwordx4 v[174:175], off
	v_lshl_add_u64 v[174:175], v[246:247], 0, s[20:21]
	s_add_i32 m0, s13, 0x2000
	s_nop 0
	global_load_lds_dwordx4 v[174:175], off
	s_add_u32 s2, s2, 0x40080
	s_addc_u32 s3, s3, 0
	s_add_i32 s12, s12, s78
	v_lshl_add_u64 v[174:175], s[2:3], 0, v[0:1]
	s_mov_b32 m0, s12
	s_nop 0
	global_load_lds_dwordx4 v[174:175], off
	v_lshl_add_u64 v[174:175], s[2:3], 0, v[166:167]
	s_add_i32 m0, s12, 0x2000
	s_nop 0
	global_load_lds_dwordx4 v[174:175], off
	s_waitcnt vmcnt(6)
	s_barrier
	s_waitcnt lgkmcnt(0)
	s_nop 0
	v_mfma_f32_16x16x32_bf16 v[94:97], v[98:101], v[114:117], v[94:97]
	v_mfma_f32_16x16x32_bf16 v[90:93], v[106:109], v[114:117], v[90:93]
	v_mfma_f32_16x16x32_bf16 v[86:89], v[98:101], v[122:125], v[86:89]
	v_mfma_f32_16x16x32_bf16 v[82:85], v[106:109], v[122:125], v[82:85]
	v_mfma_f32_16x16x32_bf16 v[78:81], v[98:101], v[186:189], v[78:81]
	v_mfma_f32_16x16x32_bf16 v[74:77], v[106:109], v[186:189], v[74:77]
	v_mfma_f32_16x16x32_bf16 v[70:73], v[98:101], v[194:197], v[70:73]
	v_mfma_f32_16x16x32_bf16 v[66:69], v[106:109], v[194:197], v[66:69]
	v_mfma_f32_16x16x32_bf16 v[94:97], v[102:105], v[118:121], v[94:97]
	v_mfma_f32_16x16x32_bf16 v[90:93], v[110:113], v[118:121], v[90:93]
	v_mfma_f32_16x16x32_bf16 v[86:89], v[102:105], v[126:129], v[86:89]
	v_mfma_f32_16x16x32_bf16 v[82:85], v[110:113], v[126:129], v[82:85]
	v_mfma_f32_16x16x32_bf16 v[78:81], v[102:105], v[190:193], v[78:81]
	v_mfma_f32_16x16x32_bf16 v[74:77], v[110:113], v[190:193], v[74:77]
	v_mfma_f32_16x16x32_bf16 v[70:73], v[102:105], v[198:201], v[70:73]
	v_mfma_f32_16x16x32_bf16 v[66:69], v[110:113], v[198:201], v[66:69]
	v_mfma_f32_16x16x32_bf16 v[30:33], v[226:229], v[114:117], v[30:33]
	v_mfma_f32_16x16x32_bf16 v[26:29], v[234:237], v[114:117], v[26:29]
	v_mfma_f32_16x16x32_bf16 v[22:25], v[226:229], v[122:125], v[22:25]
	v_mfma_f32_16x16x32_bf16 v[18:21], v[234:237], v[122:125], v[18:21]
	v_mfma_f32_16x16x32_bf16 v[14:17], v[226:229], v[186:189], v[14:17]
	v_mfma_f32_16x16x32_bf16 v[10:13], v[234:237], v[186:189], v[10:13]
	v_mfma_f32_16x16x32_bf16 v[6:9], v[226:229], v[194:197], v[6:9]
	v_mfma_f32_16x16x32_bf16 v[2:5], v[234:237], v[194:197], v[2:5]
	v_mfma_f32_16x16x32_bf16 v[30:33], v[230:233], v[118:121], v[30:33]
	v_mfma_f32_16x16x32_bf16 v[26:29], v[242:245], v[118:121], v[26:29]
	v_mfma_f32_16x16x32_bf16 v[22:25], v[230:233], v[126:129], v[22:25]
	v_mfma_f32_16x16x32_bf16 v[18:21], v[242:245], v[126:129], v[18:21]
	s_add_i32 s53, s53, 2
	s_add_u32 s34, s34, 0x100
	s_addc_u32 s35, s35, 0
	s_add_u32 s51, s51, 0x100
	s_addc_u32 s52, s52, 0
	s_cmp_gt_u32 s53, 13
	v_mfma_f32_16x16x32_bf16 v[14:17], v[230:233], v[190:193], v[14:17]
	v_mfma_f32_16x16x32_bf16 v[10:13], v[242:245], v[190:193], v[10:13]
	v_mfma_f32_16x16x32_bf16 v[6:9], v[230:233], v[198:201], v[6:9]
	v_mfma_f32_16x16x32_bf16 v[2:5], v[242:245], v[198:201], v[2:5]
	s_barrier
	s_cbranch_scc0 .LBB0_104

.LBB0_181:
	s_add_i32 s88, s44, -2
	s_add_u32 s34, s34, 0x80
	s_addc_u32 s35, s35, 0
	s_add_u32 s89, s42, 0x100
	v_mov_b32_e32 v2, 0
	s_addc_u32 s90, s43, 0
	s_mov_b32 s2, 0
	s_add_i32 s91, s2, 2
	s_add_u32 s12, s34, 0x80
	s_addc_u32 s3, s35, 0
	s_add_i32 s13, 0, 0x10000
	v_add_u32_e32 v142, s13, v183
	ds_read_b128 v[130:133], v142
	ds_read_b128 v[134:137], v142 offset:1024
	ds_read_b128 v[138:141], v142 offset:2048
	ds_read_b128 v[142:145], v142 offset:3072
	s_cmp_eq_u32 s88, s2
	s_cselect_b32 s2, s0, s12
	s_cselect_b32 s3, s1, s3
	s_cselect_b32 s43, s41, s90
	s_cselect_b32 s42, s40, s89
	v_lshl_add_u64 v[190:191], s[34:35], 0, v[174:175]
	s_add_i32 m0, s55, 0xc000
	ds_read_b128 v[146:149], v184
	ds_read_b128 v[150:153], v184 offset:1024
	ds_read_b128 v[154:157], v184 offset:2048
	ds_read_b128 v[158:161], v184 offset:3072
	ds_read_b128 v[162:165], v184 offset:4096
	ds_read_b128 v[166:169], v184 offset:5120
	ds_read_b128 v[178:181], v184 offset:6144
	ds_read_b128 v[186:189], v184 offset:7168
	global_load_lds_dwordx4 v[190:191], off
	v_lshl_add_u64 v[190:191], s[34:35], 0, v[176:177]
	s_add_i32 m0, s55, 0xe000
	s_nop 0
	global_load_lds_dwordx4 v[190:191], off
	s_waitcnt lgkmcnt(8)
	s_add_i32 s92, 0, 0x14000
	s_add_i32 s12, s13, s54
	v_add_u32_e32 v185, s92, v183
	ds_read_b128 v[190:193], v185
	ds_read_b128 v[194:197], v185 offset:1024
	ds_read_b128 v[198:201], v185 offset:2048
	ds_read_b128 v[226:229], v185 offset:3072
	s_barrier
	s_waitcnt lgkmcnt(0)
	v_mfma_f32_16x16x32_bf16 v[126:129], v[130:133], v[146:149], 0
	v_mfma_f32_16x16x32_bf16 v[122:125], v[138:141], v[146:149], 0
	v_mfma_f32_16x16x32_bf16 v[118:121], v[130:133], v[154:157], 0
	v_mfma_f32_16x16x32_bf16 v[114:117], v[138:141], v[154:157], 0
	v_mfma_f32_16x16x32_bf16 v[110:113], v[130:133], v[162:165], 0
	v_mfma_f32_16x16x32_bf16 v[106:109], v[138:141], v[162:165], 0
	v_mfma_f32_16x16x32_bf16 v[102:105], v[130:133], v[178:181], 0
	v_mfma_f32_16x16x32_bf16 v[98:101], v[138:141], v[178:181], 0
	v_mfma_f32_16x16x32_bf16 v[126:129], v[134:137], v[150:153], v[126:129]
	v_mfma_f32_16x16x32_bf16 v[122:125], v[142:145], v[150:153], v[122:125]
	v_mfma_f32_16x16x32_bf16 v[118:121], v[134:137], v[158:161], v[118:121]
	v_mfma_f32_16x16x32_bf16 v[114:117], v[142:145], v[158:161], v[114:117]
	v_mfma_f32_16x16x32_bf16 v[110:113], v[134:137], v[166:169], v[110:113]
	v_mfma_f32_16x16x32_bf16 v[106:109], v[142:145], v[166:169], v[106:109]
	v_mfma_f32_16x16x32_bf16 v[102:105], v[134:137], v[186:189], v[102:105]
	v_mfma_f32_16x16x32_bf16 v[98:101], v[142:145], v[186:189], v[98:101]
	v_mfma_f32_16x16x32_bf16 v[62:65], v[190:193], v[146:149], 0
	v_mfma_f32_16x16x32_bf16 v[58:61], v[198:201], v[146:149], 0
	v_mfma_f32_16x16x32_bf16 v[54:57], v[190:193], v[154:157], 0
	v_mfma_f32_16x16x32_bf16 v[50:53], v[198:201], v[154:157], 0
	v_mfma_f32_16x16x32_bf16 v[46:49], v[190:193], v[162:165], 0
	v_mfma_f32_16x16x32_bf16 v[42:45], v[198:201], v[162:165], 0
	v_mfma_f32_16x16x32_bf16 v[38:41], v[190:193], v[178:181], 0
	v_mfma_f32_16x16x32_bf16 v[34:37], v[198:201], v[178:181], 0
	v_mfma_f32_16x16x32_bf16 v[62:65], v[194:197], v[150:153], v[62:65]
	v_mfma_f32_16x16x32_bf16 v[58:61], v[226:229], v[150:153], v[58:61]
	v_mfma_f32_16x16x32_bf16 v[54:57], v[194:197], v[158:161], v[54:57]
	v_mfma_f32_16x16x32_bf16 v[50:53], v[226:229], v[158:161], v[50:53]
	s_mov_b32 m0, s55
	v_lshl_add_u64 v[234:235], s[2:3], 0, v[170:171]
	v_mfma_f32_16x16x32_bf16 v[46:49], v[194:197], v[166:169], v[46:49]
	v_mfma_f32_16x16x32_bf16 v[42:45], v[226:229], v[166:169], v[42:45]
	v_mfma_f32_16x16x32_bf16 v[38:41], v[194:197], v[186:189], v[38:41]
	v_mfma_f32_16x16x32_bf16 v[34:37], v[226:229], v[186:189], v[34:37]
	s_barrier
	ds_read_b128 v[146:149], v184 offset:16384
	ds_read_b128 v[150:153], v184 offset:17408
	ds_read_b128 v[154:157], v184 offset:18432
	ds_read_b128 v[158:161], v184 offset:19456
	ds_read_b128 v[162:165], v184 offset:20480
	ds_read_b128 v[166:169], v184 offset:21504
	ds_read_b128 v[178:181], v184 offset:22528
	ds_read_b128 v[186:189], v184 offset:23552
	global_load_lds_dwordx4 v[234:235], off
	v_lshl_add_u64 v[236:237], s[2:3], 0, v[172:173]
	s_mov_b32 m0, s58
	s_nop 0
	global_load_lds_dwordx4 v[236:237], off
	v_lshl_add_u64 v[230:231], s[42:43], 0, v[170:171]
	s_mov_b32 m0, s12
	s_nop 0
	global_load_lds_dwordx4 v[230:231], off
	v_lshl_add_u64 v[232:233], s[42:43], 0, v[172:173]
	s_add_i32 m0, s12, 0x2000
	s_nop 0
	global_load_lds_dwordx4 v[232:233], off
	s_add_u32 s12, s42, s18
	s_addc_u32 s13, s43, 0
	s_add_i32 s42, s92, s54
	v_lshl_add_u64 v[242:243], s[12:13], 0, v[170:171]
	s_mov_b32 m0, s42
	v_lshl_add_u64 v[244:245], s[12:13], 0, v[172:173]
	global_load_lds_dwordx4 v[242:243], off
	s_add_i32 m0, s42, 0x2000
	s_nop 0
	global_load_lds_dwordx4 v[244:245], off
	s_waitcnt vmcnt(6)
	s_barrier
	s_waitcnt lgkmcnt(0)
	s_nop 0
	v_mfma_f32_16x16x32_bf16 v[94:97], v[130:133], v[146:149], 0
	v_mfma_f32_16x16x32_bf16 v[90:93], v[138:141], v[146:149], 0
	v_mfma_f32_16x16x32_bf16 v[86:89], v[130:133], v[154:157], 0
	v_mfma_f32_16x16x32_bf16 v[82:85], v[138:141], v[154:157], 0
	v_mfma_f32_16x16x32_bf16 v[78:81], v[130:133], v[162:165], 0
	v_mfma_f32_16x16x32_bf16 v[74:77], v[138:141], v[162:165], 0
	v_mfma_f32_16x16x32_bf16 v[70:73], v[130:133], v[178:181], 0
	v_mfma_f32_16x16x32_bf16 v[66:69], v[138:141], v[178:181], 0
	v_mfma_f32_16x16x32_bf16 v[94:97], v[134:137], v[150:153], v[94:97]
	v_mfma_f32_16x16x32_bf16 v[90:93], v[142:145], v[150:153], v[90:93]
	v_mfma_f32_16x16x32_bf16 v[86:89], v[134:137], v[158:161], v[86:89]
	v_mfma_f32_16x16x32_bf16 v[82:85], v[142:145], v[158:161], v[82:85]
	v_mfma_f32_16x16x32_bf16 v[78:81], v[134:137], v[166:169], v[78:81]
	v_mfma_f32_16x16x32_bf16 v[74:77], v[142:145], v[166:169], v[74:77]
	v_mfma_f32_16x16x32_bf16 v[70:73], v[134:137], v[186:189], v[70:73]
	v_mfma_f32_16x16x32_bf16 v[66:69], v[142:145], v[186:189], v[66:69]
	v_mfma_f32_16x16x32_bf16 v[30:33], v[190:193], v[146:149], 0
	v_mfma_f32_16x16x32_bf16 v[26:29], v[198:201], v[146:149], 0
	v_mfma_f32_16x16x32_bf16 v[22:25], v[190:193], v[154:157], 0
	v_mfma_f32_16x16x32_bf16 v[18:21], v[198:201], v[154:157], 0
	v_mfma_f32_16x16x32_bf16 v[14:17], v[190:193], v[162:165], 0
	v_mfma_f32_16x16x32_bf16 v[10:13], v[198:201], v[162:165], 0
	v_mfma_f32_16x16x32_bf16 v[6:9], v[190:193], v[178:181], 0
	v_mfma_f32_16x16x32_bf16 v[2:5], v[198:201], v[178:181], 0
	v_mfma_f32_16x16x32_bf16 v[30:33], v[194:197], v[150:153], v[30:33]
	v_mfma_f32_16x16x32_bf16 v[26:29], v[226:229], v[150:153], v[26:29]
	v_mfma_f32_16x16x32_bf16 v[22:25], v[194:197], v[158:161], v[22:25]
	v_mfma_f32_16x16x32_bf16 v[18:21], v[226:229], v[158:161], v[18:21]
	s_add_i32 s12, 0, 0x18000
	v_add_u32_e32 v142, s12, v183
	v_mfma_f32_16x16x32_bf16 v[14:17], v[194:197], v[166:169], v[14:17]
	v_mfma_f32_16x16x32_bf16 v[10:13], v[226:229], v[166:169], v[10:13]
	v_mfma_f32_16x16x32_bf16 v[6:9], v[194:197], v[186:189], v[6:9]
	v_mfma_f32_16x16x32_bf16 v[2:5], v[226:229], v[186:189], v[2:5]
	s_barrier
	ds_read_b128 v[130:133], v142
	ds_read_b128 v[134:137], v142 offset:1024
	ds_read_b128 v[138:141], v142 offset:2048
	ds_read_b128 v[142:145], v142 offset:3072
	s_add_u32 s2, s2, s18
	s_addc_u32 s3, s3, 0
	s_mov_b32 m0, s59
	v_lshl_add_u64 v[190:191], s[2:3], 0, v[170:171]
	ds_read_b128 v[146:149], v184 offset:32768
	ds_read_b128 v[150:153], v184 offset:33792
	ds_read_b128 v[154:157], v184 offset:34816
	ds_read_b128 v[158:161], v184 offset:35840
	ds_read_b128 v[162:165], v184 offset:36864
	ds_read_b128 v[166:169], v184 offset:37888
	ds_read_b128 v[178:181], v184 offset:38912
	ds_read_b128 v[186:189], v184 offset:39936
	global_load_lds_dwordx4 v[190:191], off
	v_lshl_add_u64 v[190:191], s[2:3], 0, v[172:173]
	s_mov_b32 m0, s77
	s_nop 0
	global_load_lds_dwordx4 v[190:191], off
	s_waitcnt lgkmcnt(8)
	s_add_i32 s2, 0, 0x1c000
	s_add_i32 s3, s12, s54
	v_add_u32_e32 v185, s2, v183
	ds_read_b128 v[190:193], v185
	ds_read_b128 v[194:197], v185 offset:1024
	ds_read_b128 v[198:201], v185 offset:2048
	ds_read_b128 v[226:229], v185 offset:3072
	s_barrier
	s_waitcnt lgkmcnt(0)
	v_mfma_f32_16x16x32_bf16 v[126:129], v[130:133], v[146:149], v[126:129]
	v_mfma_f32_16x16x32_bf16 v[122:125], v[138:141], v[146:149], v[122:125]
	v_mfma_f32_16x16x32_bf16 v[118:121], v[130:133], v[154:157], v[118:121]
	v_mfma_f32_16x16x32_bf16 v[114:117], v[138:141], v[154:157], v[114:117]
	v_mfma_f32_16x16x32_bf16 v[110:113], v[130:133], v[162:165], v[110:113]
	v_mfma_f32_16x16x32_bf16 v[106:109], v[138:141], v[162:165], v[106:109]
	v_mfma_f32_16x16x32_bf16 v[102:105], v[130:133], v[178:181], v[102:105]
	v_mfma_f32_16x16x32_bf16 v[98:101], v[138:141], v[178:181], v[98:101]
	v_mfma_f32_16x16x32_bf16 v[126:129], v[134:137], v[150:153], v[126:129]
	v_mfma_f32_16x16x32_bf16 v[122:125], v[142:145], v[150:153], v[122:125]
	v_mfma_f32_16x16x32_bf16 v[118:121], v[134:137], v[158:161], v[118:121]
	v_mfma_f32_16x16x32_bf16 v[114:117], v[142:145], v[158:161], v[114:117]
	v_mfma_f32_16x16x32_bf16 v[110:113], v[134:137], v[166:169], v[110:113]
	v_mfma_f32_16x16x32_bf16 v[106:109], v[142:145], v[166:169], v[106:109]
	v_mfma_f32_16x16x32_bf16 v[102:105], v[134:137], v[186:189], v[102:105]
	v_mfma_f32_16x16x32_bf16 v[98:101], v[142:145], v[186:189], v[98:101]
	v_mfma_f32_16x16x32_bf16 v[62:65], v[190:193], v[146:149], v[62:65]
	v_mfma_f32_16x16x32_bf16 v[58:61], v[198:201], v[146:149], v[58:61]
	v_mfma_f32_16x16x32_bf16 v[54:57], v[190:193], v[154:157], v[54:57]
	v_mfma_f32_16x16x32_bf16 v[50:53], v[198:201], v[154:157], v[50:53]
	v_mfma_f32_16x16x32_bf16 v[46:49], v[190:193], v[162:165], v[46:49]
	v_mfma_f32_16x16x32_bf16 v[42:45], v[198:201], v[162:165], v[42:45]
	v_mfma_f32_16x16x32_bf16 v[38:41], v[190:193], v[178:181], v[38:41]
	v_mfma_f32_16x16x32_bf16 v[34:37], v[198:201], v[178:181], v[34:37]
	v_mfma_f32_16x16x32_bf16 v[62:65], v[194:197], v[150:153], v[62:65]
	v_mfma_f32_16x16x32_bf16 v[58:61], v[226:229], v[150:153], v[58:61]
	v_mfma_f32_16x16x32_bf16 v[54:57], v[194:197], v[158:161], v[54:57]
	v_mfma_f32_16x16x32_bf16 v[50:53], v[226:229], v[158:161], v[50:53]
	s_mov_b32 m0, s80
	v_lshl_add_u64 v[234:235], v[234:235], 0, s[20:21]
	v_mfma_f32_16x16x32_bf16 v[46:49], v[194:197], v[166:169], v[46:49]
	v_mfma_f32_16x16x32_bf16 v[42:45], v[226:229], v[166:169], v[42:45]
	v_mfma_f32_16x16x32_bf16 v[38:41], v[194:197], v[186:189], v[38:41]
	v_mfma_f32_16x16x32_bf16 v[34:37], v[226:229], v[186:189], v[34:37]
	s_barrier
	ds_read_b128 v[146:149], v184 offset:49152
	ds_read_b128 v[150:153], v184 offset:50176
	ds_read_b128 v[154:157], v184 offset:51200
	ds_read_b128 v[158:161], v184 offset:52224
	ds_read_b128 v[162:165], v184 offset:53248
	ds_read_b128 v[166:169], v184 offset:54272
	ds_read_b128 v[178:181], v184 offset:55296
	ds_read_b128 v[186:189], v184 offset:56320
	global_load_lds_dwordx4 v[234:235], off
	v_lshl_add_u64 v[236:237], v[236:237], 0, s[20:21]
	s_mov_b32 m0, s81
	s_nop 0
	global_load_lds_dwordx4 v[236:237], off
	v_lshl_add_u64 v[230:231], v[230:231], 0, s[20:21]
	s_mov_b32 m0, s3
	s_nop 0
	global_load_lds_dwordx4 v[230:231], off
	v_lshl_add_u64 v[230:231], v[232:233], 0, s[20:21]
	s_add_i32 m0, s3, 0x2000
	s_nop 0
	global_load_lds_dwordx4 v[230:231], off
	s_add_i32 s2, s2, s54
	v_lshl_add_u64 v[242:243], v[242:243], 0, s[20:21]
	s_mov_b32 m0, s2
	s_nop 0
	global_load_lds_dwordx4 v[242:243], off
	v_lshl_add_u64 v[244:245], v[244:245], 0, s[20:21]
	s_add_i32 m0, s2, 0x2000
	s_nop 0
	global_load_lds_dwordx4 v[244:245], off
	s_waitcnt vmcnt(6)
	s_barrier
	s_waitcnt lgkmcnt(0)
	v_mfma_f32_16x16x32_bf16 v[94:97], v[130:133], v[146:149], v[94:97]
	v_mfma_f32_16x16x32_bf16 v[90:93], v[138:141], v[146:149], v[90:93]
	v_mfma_f32_16x16x32_bf16 v[86:89], v[130:133], v[154:157], v[86:89]
	v_mfma_f32_16x16x32_bf16 v[82:85], v[138:141], v[154:157], v[82:85]
	v_mfma_f32_16x16x32_bf16 v[78:81], v[130:133], v[162:165], v[78:81]
	v_mfma_f32_16x16x32_bf16 v[74:77], v[138:141], v[162:165], v[74:77]
	v_mfma_f32_16x16x32_bf16 v[70:73], v[130:133], v[178:181], v[70:73]
	v_mfma_f32_16x16x32_bf16 v[66:69], v[138:141], v[178:181], v[66:69]
	v_mfma_f32_16x16x32_bf16 v[94:97], v[134:137], v[150:153], v[94:97]
	v_mfma_f32_16x16x32_bf16 v[90:93], v[142:145], v[150:153], v[90:93]
	v_mfma_f32_16x16x32_bf16 v[86:89], v[134:137], v[158:161], v[86:89]
	v_mfma_f32_16x16x32_bf16 v[82:85], v[142:145], v[158:161], v[82:85]
	v_mfma_f32_16x16x32_bf16 v[78:81], v[134:137], v[166:169], v[78:81]
	v_mfma_f32_16x16x32_bf16 v[74:77], v[142:145], v[166:169], v[74:77]
	v_mfma_f32_16x16x32_bf16 v[70:73], v[134:137], v[186:189], v[70:73]
	v_mfma_f32_16x16x32_bf16 v[66:69], v[142:145], v[186:189], v[66:69]
	v_mfma_f32_16x16x32_bf16 v[30:33], v[190:193], v[146:149], v[30:33]
	v_mfma_f32_16x16x32_bf16 v[26:29], v[198:201], v[146:149], v[26:29]
	v_mfma_f32_16x16x32_bf16 v[22:25], v[190:193], v[154:157], v[22:25]
	v_mfma_f32_16x16x32_bf16 v[18:21], v[198:201], v[154:157], v[18:21]
	v_mfma_f32_16x16x32_bf16 v[14:17], v[190:193], v[162:165], v[14:17]
	v_mfma_f32_16x16x32_bf16 v[10:13], v[198:201], v[162:165], v[10:13]
	v_mfma_f32_16x16x32_bf16 v[6:9], v[190:193], v[178:181], v[6:9]
	v_mfma_f32_16x16x32_bf16 v[2:5], v[198:201], v[178:181], v[2:5]
	v_mfma_f32_16x16x32_bf16 v[30:33], v[194:197], v[150:153], v[30:33]
	v_mfma_f32_16x16x32_bf16 v[26:29], v[226:229], v[150:153], v[26:29]
	v_mfma_f32_16x16x32_bf16 v[22:25], v[194:197], v[158:161], v[22:25]
	v_mfma_f32_16x16x32_bf16 v[18:21], v[226:229], v[158:161], v[18:21]
	s_add_u32 s34, s34, 0x100
	s_addc_u32 s35, s35, 0
	s_add_u32 s89, s89, 0x100
	s_addc_u32 s90, s90, 0
	s_cmp_ge_i32 s91, s44
	s_mov_b32 s2, s91
	v_mfma_f32_16x16x32_bf16 v[14:17], v[194:197], v[166:169], v[14:17]
	v_mfma_f32_16x16x32_bf16 v[10:13], v[226:229], v[166:169], v[10:13]
	v_mfma_f32_16x16x32_bf16 v[6:9], v[194:197], v[186:189], v[6:9]
	v_mfma_f32_16x16x32_bf16 v[2:5], v[226:229], v[186:189], v[2:5]
	s_barrier
	s_cbranch_scc1 .Lpeel_x_1
.LBB0_182:
	s_add_i32 s91, s2, 2
	s_add_u32 s12, s34, 0x80
	s_addc_u32 s3, s35, 0
	s_add_i32 s13, 0, 0x10000
	v_add_u32_e32 v142, s13, v183
	ds_read_b128 v[130:133], v142
	ds_read_b128 v[134:137], v142 offset:1024
	ds_read_b128 v[138:141], v142 offset:2048
	ds_read_b128 v[142:145], v142 offset:3072
	s_cmp_eq_u32 s88, s2
	s_cselect_b32 s2, s0, s12
	s_cselect_b32 s3, s1, s3
	s_cselect_b32 s43, s41, s90
	s_cselect_b32 s42, s40, s89
	v_lshl_add_u64 v[190:191], s[34:35], 0, v[174:175]
	s_add_i32 m0, s55, 0xc000
	ds_read_b128 v[146:149], v184
	ds_read_b128 v[150:153], v184 offset:1024
	ds_read_b128 v[154:157], v184 offset:2048
	ds_read_b128 v[158:161], v184 offset:3072
	ds_read_b128 v[162:165], v184 offset:4096
	ds_read_b128 v[166:169], v184 offset:5120
	ds_read_b128 v[178:181], v184 offset:6144
	ds_read_b128 v[186:189], v184 offset:7168
	global_load_lds_dwordx4 v[190:191], off
	v_lshl_add_u64 v[190:191], s[34:35], 0, v[176:177]
	s_add_i32 m0, s55, 0xe000
	s_nop 0
	global_load_lds_dwordx4 v[190:191], off
	s_waitcnt lgkmcnt(8)
	s_add_i32 s92, 0, 0x14000
	s_add_i32 s12, s13, s54
	v_add_u32_e32 v185, s92, v183
	ds_read_b128 v[190:193], v185
	ds_read_b128 v[194:197], v185 offset:1024
	ds_read_b128 v[198:201], v185 offset:2048
	ds_read_b128 v[226:229], v185 offset:3072
	s_barrier
	s_waitcnt lgkmcnt(0)
	v_mfma_f32_16x16x32_bf16 v[126:129], v[130:133], v[146:149], v[126:129]
	v_mfma_f32_16x16x32_bf16 v[122:125], v[138:141], v[146:149], v[122:125]
	v_mfma_f32_16x16x32_bf16 v[118:121], v[130:133], v[154:157], v[118:121]
	v_mfma_f32_16x16x32_bf16 v[114:117], v[138:141], v[154:157], v[114:117]
	v_mfma_f32_16x16x32_bf16 v[110:113], v[130:133], v[162:165], v[110:113]
	v_mfma_f32_16x16x32_bf16 v[106:109], v[138:141], v[162:165], v[106:109]
	v_mfma_f32_16x16x32_bf16 v[102:105], v[130:133], v[178:181], v[102:105]
	v_mfma_f32_16x16x32_bf16 v[98:101], v[138:141], v[178:181], v[98:101]
	v_mfma_f32_16x16x32_bf16 v[126:129], v[134:137], v[150:153], v[126:129]
	v_mfma_f32_16x16x32_bf16 v[122:125], v[142:145], v[150:153], v[122:125]
	v_mfma_f32_16x16x32_bf16 v[118:121], v[134:137], v[158:161], v[118:121]
	v_mfma_f32_16x16x32_bf16 v[114:117], v[142:145], v[158:161], v[114:117]
	v_mfma_f32_16x16x32_bf16 v[110:113], v[134:137], v[166:169], v[110:113]
	v_mfma_f32_16x16x32_bf16 v[106:109], v[142:145], v[166:169], v[106:109]
	v_mfma_f32_16x16x32_bf16 v[102:105], v[134:137], v[186:189], v[102:105]
	v_mfma_f32_16x16x32_bf16 v[98:101], v[142:145], v[186:189], v[98:101]
	v_mfma_f32_16x16x32_bf16 v[62:65], v[190:193], v[146:149], v[62:65]
	v_mfma_f32_16x16x32_bf16 v[58:61], v[198:201], v[146:149], v[58:61]
	v_mfma_f32_16x16x32_bf16 v[54:57], v[190:193], v[154:157], v[54:57]
	v_mfma_f32_16x16x32_bf16 v[50:53], v[198:201], v[154:157], v[50:53]
	v_mfma_f32_16x16x32_bf16 v[46:49], v[190:193], v[162:165], v[46:49]
	v_mfma_f32_16x16x32_bf16 v[42:45], v[198:201], v[162:165], v[42:45]
	v_mfma_f32_16x16x32_bf16 v[38:41], v[190:193], v[178:181], v[38:41]
	v_mfma_f32_16x16x32_bf16 v[34:37], v[198:201], v[178:181], v[34:37]
	v_mfma_f32_16x16x32_bf16 v[62:65], v[194:197], v[150:153], v[62:65]
	v_mfma_f32_16x16x32_bf16 v[58:61], v[226:229], v[150:153], v[58:61]
	v_mfma_f32_16x16x32_bf16 v[54:57], v[194:197], v[158:161], v[54:57]
	v_mfma_f32_16x16x32_bf16 v[50:53], v[226:229], v[158:161], v[50:53]
	s_mov_b32 m0, s55
	v_lshl_add_u64 v[234:235], s[2:3], 0, v[170:171]
	v_mfma_f32_16x16x32_bf16 v[46:49], v[194:197], v[166:169], v[46:49]
	v_mfma_f32_16x16x32_bf16 v[42:45], v[226:229], v[166:169], v[42:45]
	v_mfma_f32_16x16x32_bf16 v[38:41], v[194:197], v[186:189], v[38:41]
	v_mfma_f32_16x16x32_bf16 v[34:37], v[226:229], v[186:189], v[34:37]
	s_barrier
	ds_read_b128 v[146:149], v184 offset:16384
	ds_read_b128 v[150:153], v184 offset:17408
	ds_read_b128 v[154:157], v184 offset:18432
	ds_read_b128 v[158:161], v184 offset:19456
	ds_read_b128 v[162:165], v184 offset:20480
	ds_read_b128 v[166:169], v184 offset:21504
	ds_read_b128 v[178:181], v184 offset:22528
	ds_read_b128 v[186:189], v184 offset:23552
	global_load_lds_dwordx4 v[234:235], off
	v_lshl_add_u64 v[236:237], s[2:3], 0, v[172:173]
	s_mov_b32 m0, s58
	s_nop 0
	global_load_lds_dwordx4 v[236:237], off
	v_lshl_add_u64 v[230:231], s[42:43], 0, v[170:171]
	s_mov_b32 m0, s12
	s_nop 0
	global_load_lds_dwordx4 v[230:231], off
	v_lshl_add_u64 v[232:233], s[42:43], 0, v[172:173]
	s_add_i32 m0, s12, 0x2000
	s_nop 0
	global_load_lds_dwordx4 v[232:233], off
	s_add_u32 s12, s42, s18
	s_addc_u32 s13, s43, 0
	s_add_i32 s42, s92, s54
	v_lshl_add_u64 v[242:243], s[12:13], 0, v[170:171]
	s_mov_b32 m0, s42
	v_lshl_add_u64 v[244:245], s[12:13], 0, v[172:173]
	global_load_lds_dwordx4 v[242:243], off
	s_add_i32 m0, s42, 0x2000
	s_nop 0
	global_load_lds_dwordx4 v[244:245], off
	s_waitcnt vmcnt(6)
	s_barrier
	s_waitcnt lgkmcnt(0)
	s_nop 0
	v_mfma_f32_16x16x32_bf16 v[94:97], v[130:133], v[146:149], v[94:97]
	v_mfma_f32_16x16x32_bf16 v[90:93], v[138:141], v[146:149], v[90:93]
	v_mfma_f32_16x16x32_bf16 v[86:89], v[130:133], v[154:157], v[86:89]
	v_mfma_f32_16x16x32_bf16 v[82:85], v[138:141], v[154:157], v[82:85]
	v_mfma_f32_16x16x32_bf16 v[78:81], v[130:133], v[162:165], v[78:81]
	v_mfma_f32_16x16x32_bf16 v[74:77], v[138:141], v[162:165], v[74:77]
	v_mfma_f32_16x16x32_bf16 v[70:73], v[130:133], v[178:181], v[70:73]
	v_mfma_f32_16x16x32_bf16 v[66:69], v[138:141], v[178:181], v[66:69]
	v_mfma_f32_16x16x32_bf16 v[94:97], v[134:137], v[150:153], v[94:97]
	v_mfma_f32_16x16x32_bf16 v[90:93], v[142:145], v[150:153], v[90:93]
	v_mfma_f32_16x16x32_bf16 v[86:89], v[134:137], v[158:161], v[86:89]
	v_mfma_f32_16x16x32_bf16 v[82:85], v[142:145], v[158:161], v[82:85]
	v_mfma_f32_16x16x32_bf16 v[78:81], v[134:137], v[166:169], v[78:81]
	v_mfma_f32_16x16x32_bf16 v[74:77], v[142:145], v[166:169], v[74:77]
	v_mfma_f32_16x16x32_bf16 v[70:73], v[134:137], v[186:189], v[70:73]
	v_mfma_f32_16x16x32_bf16 v[66:69], v[142:145], v[186:189], v[66:69]
	v_mfma_f32_16x16x32_bf16 v[30:33], v[190:193], v[146:149], v[30:33]
	v_mfma_f32_16x16x32_bf16 v[26:29], v[198:201], v[146:149], v[26:29]
	v_mfma_f32_16x16x32_bf16 v[22:25], v[190:193], v[154:157], v[22:25]
	v_mfma_f32_16x16x32_bf16 v[18:21], v[198:201], v[154:157], v[18:21]
	v_mfma_f32_16x16x32_bf16 v[14:17], v[190:193], v[162:165], v[14:17]
	v_mfma_f32_16x16x32_bf16 v[10:13], v[198:201], v[162:165], v[10:13]
	v_mfma_f32_16x16x32_bf16 v[6:9], v[190:193], v[178:181], v[6:9]
	v_mfma_f32_16x16x32_bf16 v[2:5], v[198:201], v[178:181], v[2:5]
	v_mfma_f32_16x16x32_bf16 v[30:33], v[194:197], v[150:153], v[30:33]
	v_mfma_f32_16x16x32_bf16 v[26:29], v[226:229], v[150:153], v[26:29]
	v_mfma_f32_16x16x32_bf16 v[22:25], v[194:197], v[158:161], v[22:25]
	v_mfma_f32_16x16x32_bf16 v[18:21], v[226:229], v[158:161], v[18:21]
	s_add_i32 s12, 0, 0x18000
	v_add_u32_e32 v142, s12, v183
	v_mfma_f32_16x16x32_bf16 v[14:17], v[194:197], v[166:169], v[14:17]
	v_mfma_f32_16x16x32_bf16 v[10:13], v[226:229], v[166:169], v[10:13]
	v_mfma_f32_16x16x32_bf16 v[6:9], v[194:197], v[186:189], v[6:9]
	v_mfma_f32_16x16x32_bf16 v[2:5], v[226:229], v[186:189], v[2:5]
	s_barrier
	ds_read_b128 v[130:133], v142
	ds_read_b128 v[134:137], v142 offset:1024
	ds_read_b128 v[138:141], v142 offset:2048
	ds_read_b128 v[142:145], v142 offset:3072
	s_add_u32 s2, s2, s18
	s_addc_u32 s3, s3, 0
	s_mov_b32 m0, s59
	v_lshl_add_u64 v[190:191], s[2:3], 0, v[170:171]
	ds_read_b128 v[146:149], v184 offset:32768
	ds_read_b128 v[150:153], v184 offset:33792
	ds_read_b128 v[154:157], v184 offset:34816
	ds_read_b128 v[158:161], v184 offset:35840
	ds_read_b128 v[162:165], v184 offset:36864
	ds_read_b128 v[166:169], v184 offset:37888
	ds_read_b128 v[178:181], v184 offset:38912
	ds_read_b128 v[186:189], v184 offset:39936
	global_load_lds_dwordx4 v[190:191], off
	v_lshl_add_u64 v[190:191], s[2:3], 0, v[172:173]
	s_mov_b32 m0, s77
	s_nop 0
	global_load_lds_dwordx4 v[190:191], off
	s_waitcnt lgkmcnt(8)
	s_add_i32 s2, 0, 0x1c000
	s_add_i32 s3, s12, s54
	v_add_u32_e32 v185, s2, v183
	ds_read_b128 v[190:193], v185
	ds_read_b128 v[194:197], v185 offset:1024
	ds_read_b128 v[198:201], v185 offset:2048
	ds_read_b128 v[226:229], v185 offset:3072
	s_barrier
	s_waitcnt lgkmcnt(0)
	v_mfma_f32_16x16x32_bf16 v[126:129], v[130:133], v[146:149], v[126:129]
	v_mfma_f32_16x16x32_bf16 v[122:125], v[138:141], v[146:149], v[122:125]
	v_mfma_f32_16x16x32_bf16 v[118:121], v[130:133], v[154:157], v[118:121]
	v_mfma_f32_16x16x32_bf16 v[114:117], v[138:141], v[154:157], v[114:117]
	v_mfma_f32_16x16x32_bf16 v[110:113], v[130:133], v[162:165], v[110:113]
	v_mfma_f32_16x16x32_bf16 v[106:109], v[138:141], v[162:165], v[106:109]
	v_mfma_f32_16x16x32_bf16 v[102:105], v[130:133], v[178:181], v[102:105]
	v_mfma_f32_16x16x32_bf16 v[98:101], v[138:141], v[178:181], v[98:101]
	v_mfma_f32_16x16x32_bf16 v[126:129], v[134:137], v[150:153], v[126:129]
	v_mfma_f32_16x16x32_bf16 v[122:125], v[142:145], v[150:153], v[122:125]
	v_mfma_f32_16x16x32_bf16 v[118:121], v[134:137], v[158:161], v[118:121]
	v_mfma_f32_16x16x32_bf16 v[114:117], v[142:145], v[158:161], v[114:117]
	v_mfma_f32_16x16x32_bf16 v[110:113], v[134:137], v[166:169], v[110:113]
	v_mfma_f32_16x16x32_bf16 v[106:109], v[142:145], v[166:169], v[106:109]
	v_mfma_f32_16x16x32_bf16 v[102:105], v[134:137], v[186:189], v[102:105]
	v_mfma_f32_16x16x32_bf16 v[98:101], v[142:145], v[186:189], v[98:101]
	v_mfma_f32_16x16x32_bf16 v[62:65], v[190:193], v[146:149], v[62:65]
	v_mfma_f32_16x16x32_bf16 v[58:61], v[198:201], v[146:149], v[58:61]
	v_mfma_f32_16x16x32_bf16 v[54:57], v[190:193], v[154:157], v[54:57]
	v_mfma_f32_16x16x32_bf16 v[50:53], v[198:201], v[154:157], v[50:53]
	v_mfma_f32_16x16x32_bf16 v[46:49], v[190:193], v[162:165], v[46:49]
	v_mfma_f32_16x16x32_bf16 v[42:45], v[198:201], v[162:165], v[42:45]
	v_mfma_f32_16x16x32_bf16 v[38:41], v[190:193], v[178:181], v[38:41]
	v_mfma_f32_16x16x32_bf16 v[34:37], v[198:201], v[178:181], v[34:37]
	v_mfma_f32_16x16x32_bf16 v[62:65], v[194:197], v[150:153], v[62:65]
	v_mfma_f32_16x16x32_bf16 v[58:61], v[226:229], v[150:153], v[58:61]
	v_mfma_f32_16x16x32_bf16 v[54:57], v[194:197], v[158:161], v[54:57]
	v_mfma_f32_16x16x32_bf16 v[50:53], v[226:229], v[158:161], v[50:53]
	s_mov_b32 m0, s80
	v_lshl_add_u64 v[234:235], v[234:235], 0, s[20:21]
	v_mfma_f32_16x16x32_bf16 v[46:49], v[194:197], v[166:169], v[46:49]
	v_mfma_f32_16x16x32_bf16 v[42:45], v[226:229], v[166:169], v[42:45]
	v_mfma_f32_16x16x32_bf16 v[38:41], v[194:197], v[186:189], v[38:41]
	v_mfma_f32_16x16x32_bf16 v[34:37], v[226:229], v[186:189], v[34:37]
	s_barrier
	ds_read_b128 v[146:149], v184 offset:49152
	ds_read_b128 v[150:153], v184 offset:50176
	ds_read_b128 v[154:157], v184 offset:51200
	ds_read_b128 v[158:161], v184 offset:52224
	ds_read_b128 v[162:165], v184 offset:53248
	ds_read_b128 v[166:169], v184 offset:54272
	ds_read_b128 v[178:181], v184 offset:55296
	ds_read_b128 v[186:189], v184 offset:56320
	global_load_lds_dwordx4 v[234:235], off
	v_lshl_add_u64 v[236:237], v[236:237], 0, s[20:21]
	s_mov_b32 m0, s81
	s_nop 0
	global_load_lds_dwordx4 v[236:237], off
	v_lshl_add_u64 v[230:231], v[230:231], 0, s[20:21]
	s_mov_b32 m0, s3
	s_nop 0
	global_load_lds_dwordx4 v[230:231], off
	v_lshl_add_u64 v[230:231], v[232:233], 0, s[20:21]
	s_add_i32 m0, s3, 0x2000
	s_nop 0
	global_load_lds_dwordx4 v[230:231], off
	s_add_i32 s2, s2, s54
	v_lshl_add_u64 v[242:243], v[242:243], 0, s[20:21]
	s_mov_b32 m0, s2
	s_nop 0
	global_load_lds_dwordx4 v[242:243], off
	v_lshl_add_u64 v[244:245], v[244:245], 0, s[20:21]
	s_add_i32 m0, s2, 0x2000
	s_nop 0
	global_load_lds_dwordx4 v[244:245], off
	s_waitcnt vmcnt(6)
	s_barrier
	s_waitcnt lgkmcnt(0)
	v_mfma_f32_16x16x32_bf16 v[94:97], v[130:133], v[146:149], v[94:97]
	v_mfma_f32_16x16x32_bf16 v[90:93], v[138:141], v[146:149], v[90:93]
	v_mfma_f32_16x16x32_bf16 v[86:89], v[130:133], v[154:157], v[86:89]
	v_mfma_f32_16x16x32_bf16 v[82:85], v[138:141], v[154:157], v[82:85]
	v_mfma_f32_16x16x32_bf16 v[78:81], v[130:133], v[162:165], v[78:81]
	v_mfma_f32_16x16x32_bf16 v[74:77], v[138:141], v[162:165], v[74:77]
	v_mfma_f32_16x16x32_bf16 v[70:73], v[130:133], v[178:181], v[70:73]
	v_mfma_f32_16x16x32_bf16 v[66:69], v[138:141], v[178:181], v[66:69]
	v_mfma_f32_16x16x32_bf16 v[94:97], v[134:137], v[150:153], v[94:97]
	v_mfma_f32_16x16x32_bf16 v[90:93], v[142:145], v[150:153], v[90:93]
	v_mfma_f32_16x16x32_bf16 v[86:89], v[134:137], v[158:161], v[86:89]
	v_mfma_f32_16x16x32_bf16 v[82:85], v[142:145], v[158:161], v[82:85]
	v_mfma_f32_16x16x32_bf16 v[78:81], v[134:137], v[166:169], v[78:81]
	v_mfma_f32_16x16x32_bf16 v[74:77], v[142:145], v[166:169], v[74:77]
	v_mfma_f32_16x16x32_bf16 v[70:73], v[134:137], v[186:189], v[70:73]
	v_mfma_f32_16x16x32_bf16 v[66:69], v[142:145], v[186:189], v[66:69]
	v_mfma_f32_16x16x32_bf16 v[30:33], v[190:193], v[146:149], v[30:33]
	v_mfma_f32_16x16x32_bf16 v[26:29], v[198:201], v[146:149], v[26:29]
	v_mfma_f32_16x16x32_bf16 v[22:25], v[190:193], v[154:157], v[22:25]
	v_mfma_f32_16x16x32_bf16 v[18:21], v[198:201], v[154:157], v[18:21]
	v_mfma_f32_16x16x32_bf16 v[14:17], v[190:193], v[162:165], v[14:17]
	v_mfma_f32_16x16x32_bf16 v[10:13], v[198:201], v[162:165], v[10:13]
	v_mfma_f32_16x16x32_bf16 v[6:9], v[190:193], v[178:181], v[6:9]
	v_mfma_f32_16x16x32_bf16 v[2:5], v[198:201], v[178:181], v[2:5]
	v_mfma_f32_16x16x32_bf16 v[30:33], v[194:197], v[150:153], v[30:33]
	v_mfma_f32_16x16x32_bf16 v[26:29], v[226:229], v[150:153], v[26:29]
	v_mfma_f32_16x16x32_bf16 v[22:25], v[194:197], v[158:161], v[22:25]
	v_mfma_f32_16x16x32_bf16 v[18:21], v[226:229], v[158:161], v[18:21]
	s_add_u32 s34, s34, 0x100
	s_addc_u32 s35, s35, 0
	s_add_u32 s89, s89, 0x100
	s_addc_u32 s90, s90, 0
	s_cmp_ge_i32 s91, s44
	s_mov_b32 s2, s91
	v_mfma_f32_16x16x32_bf16 v[14:17], v[194:197], v[166:169], v[14:17]
	v_mfma_f32_16x16x32_bf16 v[10:13], v[226:229], v[166:169], v[10:13]
	v_mfma_f32_16x16x32_bf16 v[6:9], v[194:197], v[186:189], v[6:9]
	v_mfma_f32_16x16x32_bf16 v[2:5], v[226:229], v[186:189], v[2:5]
	s_barrier
	s_cbranch_scc0 .LBB0_182

.LBB0_366:
	s_add_u32 s2, s0, 0xfffc0080
	s_addc_u32 s3, s1, -1
	s_add_i32 s12, 0, 0x10000
	v_add_u32_e32 v142, s12, v227
	ds_read_b128 v[130:133], v142
	ds_read_b128 v[134:137], v142 offset:1024
	ds_read_b128 v[138:141], v142 offset:2048
	ds_read_b128 v[142:145], v142 offset:3072
	s_cmp_eq_u32 s47, 12
	s_cselect_b32 s17, s15, s3
	s_cselect_b32 s16, s19, s2
	s_cselect_b32 s3, s43, s46
	s_cselect_b32 s2, s44, s45
	v_lshl_add_u64 v[190:191], s[0:1], 0, v[162:163]
	s_add_i32 m0, s54, 0xc000
	ds_read_b128 v[146:149], v233
	ds_read_b128 v[150:153], v233 offset:1024
	ds_read_b128 v[166:169], v233 offset:2048
	ds_read_b128 v[170:173], v233 offset:3072
	ds_read_b128 v[174:177], v233 offset:4096
	ds_read_b128 v[178:181], v233 offset:5120
	ds_read_b128 v[182:185], v233 offset:6144
	ds_read_b128 v[186:189], v233 offset:7168
	global_load_lds_dwordx4 v[190:191], off
	v_lshl_add_u64 v[190:191], s[0:1], 0, v[164:165]
	s_add_i32 m0, s54, 0xe000
	s_nop 0
	global_load_lds_dwordx4 v[190:191], off
	s_waitcnt lgkmcnt(8)
	s_barrier
	s_waitcnt lgkmcnt(0)
	v_mfma_f32_16x16x32_bf16 v[126:129], v[130:133], v[146:149], v[126:129]
	v_mfma_f32_16x16x32_bf16 v[122:125], v[138:141], v[146:149], v[122:125]
	v_mfma_f32_16x16x32_bf16 v[118:121], v[130:133], v[166:169], v[118:121]
	v_mfma_f32_16x16x32_bf16 v[114:117], v[138:141], v[166:169], v[114:117]
	v_mfma_f32_16x16x32_bf16 v[110:113], v[130:133], v[174:177], v[110:113]
	v_mfma_f32_16x16x32_bf16 v[106:109], v[138:141], v[174:177], v[106:109]
	v_mfma_f32_16x16x32_bf16 v[102:105], v[130:133], v[182:185], v[102:105]
	v_mfma_f32_16x16x32_bf16 v[98:101], v[138:141], v[182:185], v[98:101]
	v_mfma_f32_16x16x32_bf16 v[126:129], v[134:137], v[150:153], v[126:129]
	v_mfma_f32_16x16x32_bf16 v[122:125], v[142:145], v[150:153], v[122:125]
	v_mfma_f32_16x16x32_bf16 v[118:121], v[134:137], v[170:173], v[118:121]
	v_mfma_f32_16x16x32_bf16 v[114:117], v[142:145], v[170:173], v[114:117]
	v_mfma_f32_16x16x32_bf16 v[110:113], v[134:137], v[178:181], v[110:113]
	v_mfma_f32_16x16x32_bf16 v[106:109], v[142:145], v[178:181], v[106:109]
	v_mfma_f32_16x16x32_bf16 v[102:105], v[134:137], v[186:189], v[102:105]
	v_mfma_f32_16x16x32_bf16 v[98:101], v[142:145], v[186:189], v[98:101]
	s_barrier
	s_add_i32 s13, 0, 0x14000
	s_add_i32 s12, s12, s35
	v_add_u32_e32 v234, s13, v227
	v_lshl_add_u64 v[242:243], s[2:3], 0, v[0:1]
	s_mov_b32 m0, s12
	ds_read_b128 v[190:193], v234
	ds_read_b128 v[194:197], v234 offset:1024
	ds_read_b128 v[198:201], v234 offset:2048
	ds_read_b128 v[234:237], v234 offset:3072
	global_load_lds_dwordx4 v[242:243], off
	v_lshl_add_u64 v[244:245], s[2:3], 0, v[154:155]
	s_add_i32 m0, s12, 0x2000
	s_nop 0
	global_load_lds_dwordx4 v[244:245], off
	s_barrier
	s_waitcnt lgkmcnt(0)
	s_nop 0
	v_mfma_f32_16x16x32_bf16 v[62:65], v[190:193], v[146:149], v[62:65]
	v_mfma_f32_16x16x32_bf16 v[58:61], v[198:201], v[146:149], v[58:61]
	v_mfma_f32_16x16x32_bf16 v[54:57], v[190:193], v[166:169], v[54:57]
	v_mfma_f32_16x16x32_bf16 v[50:53], v[198:201], v[166:169], v[50:53]
	v_mfma_f32_16x16x32_bf16 v[46:49], v[190:193], v[174:177], v[46:49]
	v_mfma_f32_16x16x32_bf16 v[42:45], v[198:201], v[174:177], v[42:45]
	v_mfma_f32_16x16x32_bf16 v[38:41], v[190:193], v[182:185], v[38:41]
	v_mfma_f32_16x16x32_bf16 v[34:37], v[198:201], v[182:185], v[34:37]
	v_mfma_f32_16x16x32_bf16 v[62:65], v[194:197], v[150:153], v[62:65]
	v_mfma_f32_16x16x32_bf16 v[58:61], v[234:237], v[150:153], v[58:61]
	v_mfma_f32_16x16x32_bf16 v[54:57], v[194:197], v[170:173], v[54:57]
	v_mfma_f32_16x16x32_bf16 v[50:53], v[234:237], v[170:173], v[50:53]
	s_mov_b32 m0, s54
	v_mfma_f32_16x16x32_bf16 v[46:49], v[194:197], v[178:181], v[46:49]
	v_mfma_f32_16x16x32_bf16 v[42:45], v[234:237], v[178:181], v[42:45]
	v_mfma_f32_16x16x32_bf16 v[38:41], v[194:197], v[186:189], v[38:41]
	v_mfma_f32_16x16x32_bf16 v[34:37], v[234:237], v[186:189], v[34:37]
	s_barrier
	ds_read_b128 v[146:149], v233 offset:16384
	ds_read_b128 v[150:153], v233 offset:17408
	ds_read_b128 v[166:169], v233 offset:18432
	ds_read_b128 v[170:173], v233 offset:19456
	ds_read_b128 v[174:177], v233 offset:20480
	ds_read_b128 v[178:181], v233 offset:21504
	ds_read_b128 v[182:185], v233 offset:22528
	ds_read_b128 v[186:189], v233 offset:23552
	global_load_lds_dwordx4 v250, s[16:17]
	s_nop 0
	s_mov_b32 m0, s55
	s_nop 0
	global_load_lds_dwordx4 v251, s[16:17]
	s_barrier
	s_waitcnt lgkmcnt(0)
	s_nop 0
	v_mfma_f32_16x16x32_bf16 v[94:97], v[130:133], v[146:149], v[94:97]
	v_mfma_f32_16x16x32_bf16 v[90:93], v[138:141], v[146:149], v[90:93]
	v_mfma_f32_16x16x32_bf16 v[86:89], v[130:133], v[166:169], v[86:89]
	v_mfma_f32_16x16x32_bf16 v[82:85], v[138:141], v[166:169], v[82:85]
	v_mfma_f32_16x16x32_bf16 v[78:81], v[130:133], v[174:177], v[78:81]
	v_mfma_f32_16x16x32_bf16 v[74:77], v[138:141], v[174:177], v[74:77]
	v_mfma_f32_16x16x32_bf16 v[70:73], v[130:133], v[182:185], v[70:73]
	v_mfma_f32_16x16x32_bf16 v[66:69], v[138:141], v[182:185], v[66:69]
	v_mfma_f32_16x16x32_bf16 v[94:97], v[134:137], v[150:153], v[94:97]
	v_mfma_f32_16x16x32_bf16 v[90:93], v[142:145], v[150:153], v[90:93]
	v_mfma_f32_16x16x32_bf16 v[86:89], v[134:137], v[170:173], v[86:89]
	v_mfma_f32_16x16x32_bf16 v[82:85], v[142:145], v[170:173], v[82:85]
	v_mfma_f32_16x16x32_bf16 v[78:81], v[134:137], v[178:181], v[78:81]
	v_mfma_f32_16x16x32_bf16 v[74:77], v[142:145], v[178:181], v[74:77]
	v_mfma_f32_16x16x32_bf16 v[70:73], v[134:137], v[186:189], v[70:73]
	v_mfma_f32_16x16x32_bf16 v[66:69], v[142:145], v[186:189], v[66:69]
	s_barrier
	s_add_u32 s78, s2, 0x40000
	s_addc_u32 s79, s3, 0
	s_add_i32 s12, s13, s35
	v_lshl_add_u64 v[130:131], s[78:79], 0, v[0:1]
	s_mov_b32 m0, s12
	s_nop 0
	global_load_lds_dwordx4 v[130:131], off
	v_lshl_add_u64 v[130:131], s[78:79], 0, v[154:155]
	s_add_i32 m0, s12, 0x2000
	s_nop 0
	global_load_lds_dwordx4 v[130:131], off
	s_waitcnt vmcnt(6)
	s_barrier
	v_mfma_f32_16x16x32_bf16 v[30:33], v[190:193], v[146:149], v[30:33]
	v_mfma_f32_16x16x32_bf16 v[26:29], v[198:201], v[146:149], v[26:29]
	v_mfma_f32_16x16x32_bf16 v[22:25], v[190:193], v[166:169], v[22:25]
	v_mfma_f32_16x16x32_bf16 v[18:21], v[198:201], v[166:169], v[18:21]
	v_mfma_f32_16x16x32_bf16 v[14:17], v[190:193], v[174:177], v[14:17]
	v_mfma_f32_16x16x32_bf16 v[10:13], v[198:201], v[174:177], v[10:13]
	v_mfma_f32_16x16x32_bf16 v[6:9], v[190:193], v[182:185], v[6:9]
	v_mfma_f32_16x16x32_bf16 v[2:5], v[198:201], v[182:185], v[2:5]
	v_mfma_f32_16x16x32_bf16 v[30:33], v[194:197], v[150:153], v[30:33]
	v_mfma_f32_16x16x32_bf16 v[26:29], v[234:237], v[150:153], v[26:29]
	v_mfma_f32_16x16x32_bf16 v[22:25], v[194:197], v[170:173], v[22:25]
	v_mfma_f32_16x16x32_bf16 v[18:21], v[234:237], v[170:173], v[18:21]
	s_add_i32 s12, 0, 0x18000
	v_add_u32_e32 v142, s12, v227
	v_mfma_f32_16x16x32_bf16 v[14:17], v[194:197], v[178:181], v[14:17]
	v_mfma_f32_16x16x32_bf16 v[10:13], v[234:237], v[178:181], v[10:13]
	v_mfma_f32_16x16x32_bf16 v[6:9], v[194:197], v[186:189], v[6:9]
	v_mfma_f32_16x16x32_bf16 v[2:5], v[234:237], v[186:189], v[2:5]
	s_barrier
	ds_read_b128 v[130:133], v142
	ds_read_b128 v[134:137], v142 offset:1024
	ds_read_b128 v[138:141], v142 offset:2048
	ds_read_b128 v[142:145], v142 offset:3072
	s_add_u32 s16, s16, 0x40000
	s_addc_u32 s17, s17, 0
	s_mov_b32 m0, s58
	s_nop 0
	ds_read_b128 v[146:149], v233 offset:32768
	ds_read_b128 v[150:153], v233 offset:33792
	ds_read_b128 v[166:169], v233 offset:34816
	ds_read_b128 v[170:173], v233 offset:35840
	ds_read_b128 v[174:177], v233 offset:36864
	ds_read_b128 v[178:181], v233 offset:37888
	ds_read_b128 v[182:185], v233 offset:38912
	ds_read_b128 v[186:189], v233 offset:39936
	global_load_lds_dwordx4 v250, s[16:17]
	s_nop 0
	s_mov_b32 m0, s59
	s_nop 0
	global_load_lds_dwordx4 v251, s[16:17]
	s_waitcnt lgkmcnt(8)
	s_barrier
	s_waitcnt lgkmcnt(0)
	s_nop 0
	v_mfma_f32_16x16x32_bf16 v[126:129], v[130:133], v[146:149], v[126:129]
	v_mfma_f32_16x16x32_bf16 v[122:125], v[138:141], v[146:149], v[122:125]
	v_mfma_f32_16x16x32_bf16 v[118:121], v[130:133], v[166:169], v[118:121]
	v_mfma_f32_16x16x32_bf16 v[114:117], v[138:141], v[166:169], v[114:117]
	v_mfma_f32_16x16x32_bf16 v[110:113], v[130:133], v[174:177], v[110:113]
	v_mfma_f32_16x16x32_bf16 v[106:109], v[138:141], v[174:177], v[106:109]
	v_mfma_f32_16x16x32_bf16 v[102:105], v[130:133], v[182:185], v[102:105]
	v_mfma_f32_16x16x32_bf16 v[98:101], v[138:141], v[182:185], v[98:101]
	v_mfma_f32_16x16x32_bf16 v[126:129], v[134:137], v[150:153], v[126:129]
	v_mfma_f32_16x16x32_bf16 v[122:125], v[142:145], v[150:153], v[122:125]
	v_mfma_f32_16x16x32_bf16 v[118:121], v[134:137], v[170:173], v[118:121]
	v_mfma_f32_16x16x32_bf16 v[114:117], v[142:145], v[170:173], v[114:117]
	v_mfma_f32_16x16x32_bf16 v[110:113], v[134:137], v[178:181], v[110:113]
	v_mfma_f32_16x16x32_bf16 v[106:109], v[142:145], v[178:181], v[106:109]
	v_mfma_f32_16x16x32_bf16 v[102:105], v[134:137], v[186:189], v[102:105]
	v_mfma_f32_16x16x32_bf16 v[98:101], v[142:145], v[186:189], v[98:101]
	s_barrier
	s_add_i32 s13, 0, 0x1c000
	s_add_i32 s12, s12, s35
	v_add_u32_e32 v234, s13, v227
	v_lshl_add_u64 v[242:243], v[242:243], 0, s[20:21]
	s_mov_b32 m0, s12
	ds_read_b128 v[190:193], v234
	ds_read_b128 v[194:197], v234 offset:1024
	ds_read_b128 v[198:201], v234 offset:2048
	ds_read_b128 v[234:237], v234 offset:3072
	global_load_lds_dwordx4 v[242:243], off
	v_lshl_add_u64 v[242:243], v[244:245], 0, s[20:21]
	s_add_i32 m0, s12, 0x2000
	s_nop 0
	global_load_lds_dwordx4 v[242:243], off
	s_barrier
	s_waitcnt lgkmcnt(0)
	s_nop 0
	v_mfma_f32_16x16x32_bf16 v[62:65], v[190:193], v[146:149], v[62:65]
	v_mfma_f32_16x16x32_bf16 v[58:61], v[198:201], v[146:149], v[58:61]
	v_mfma_f32_16x16x32_bf16 v[54:57], v[190:193], v[166:169], v[54:57]
	v_mfma_f32_16x16x32_bf16 v[50:53], v[198:201], v[166:169], v[50:53]
	v_mfma_f32_16x16x32_bf16 v[46:49], v[190:193], v[174:177], v[46:49]
	v_mfma_f32_16x16x32_bf16 v[42:45], v[198:201], v[174:177], v[42:45]
	v_mfma_f32_16x16x32_bf16 v[38:41], v[190:193], v[182:185], v[38:41]
	v_mfma_f32_16x16x32_bf16 v[34:37], v[198:201], v[182:185], v[34:37]
	v_mfma_f32_16x16x32_bf16 v[62:65], v[194:197], v[150:153], v[62:65]
	v_mfma_f32_16x16x32_bf16 v[58:61], v[234:237], v[150:153], v[58:61]
	v_mfma_f32_16x16x32_bf16 v[54:57], v[194:197], v[170:173], v[54:57]
	v_mfma_f32_16x16x32_bf16 v[50:53], v[234:237], v[170:173], v[50:53]
	s_mov_b32 m0, s96
	s_add_u32 s78, s16, 0xfffc0080
	s_addc_u32 s79, s17, -1
	v_mfma_f32_16x16x32_bf16 v[46:49], v[194:197], v[178:181], v[46:49]
	v_mfma_f32_16x16x32_bf16 v[42:45], v[234:237], v[178:181], v[42:45]
	v_mfma_f32_16x16x32_bf16 v[38:41], v[194:197], v[186:189], v[38:41]
	v_mfma_f32_16x16x32_bf16 v[34:37], v[234:237], v[186:189], v[34:37]
	s_barrier
	ds_read_b128 v[146:149], v233 offset:49152
	ds_read_b128 v[150:153], v233 offset:50176
	ds_read_b128 v[166:169], v233 offset:51200
	ds_read_b128 v[170:173], v233 offset:52224
	ds_read_b128 v[174:177], v233 offset:53248
	ds_read_b128 v[178:181], v233 offset:54272
	ds_read_b128 v[182:185], v233 offset:55296
	ds_read_b128 v[186:189], v233 offset:56320
	global_load_lds_dwordx4 v250, s[78:79]
	s_nop 0
	s_mov_b32 m0, s97
	s_nop 0
	global_load_lds_dwordx4 v251, s[78:79]
	s_barrier
	s_waitcnt lgkmcnt(0)
	v_mfma_f32_16x16x32_bf16 v[94:97], v[130:133], v[146:149], v[94:97]
	v_mfma_f32_16x16x32_bf16 v[90:93], v[138:141], v[146:149], v[90:93]
	v_mfma_f32_16x16x32_bf16 v[86:89], v[130:133], v[166:169], v[86:89]
	v_mfma_f32_16x16x32_bf16 v[82:85], v[138:141], v[166:169], v[82:85]
	v_mfma_f32_16x16x32_bf16 v[78:81], v[130:133], v[174:177], v[78:81]
	v_mfma_f32_16x16x32_bf16 v[74:77], v[138:141], v[174:177], v[74:77]
	v_mfma_f32_16x16x32_bf16 v[70:73], v[130:133], v[182:185], v[70:73]
	v_mfma_f32_16x16x32_bf16 v[66:69], v[138:141], v[182:185], v[66:69]
	v_mfma_f32_16x16x32_bf16 v[94:97], v[134:137], v[150:153], v[94:97]
	v_mfma_f32_16x16x32_bf16 v[90:93], v[142:145], v[150:153], v[90:93]
	v_mfma_f32_16x16x32_bf16 v[86:89], v[134:137], v[170:173], v[86:89]
	v_mfma_f32_16x16x32_bf16 v[82:85], v[142:145], v[170:173], v[82:85]
	v_mfma_f32_16x16x32_bf16 v[78:81], v[134:137], v[178:181], v[78:81]
	v_mfma_f32_16x16x32_bf16 v[74:77], v[142:145], v[178:181], v[74:77]
	v_mfma_f32_16x16x32_bf16 v[70:73], v[134:137], v[186:189], v[70:73]
	v_mfma_f32_16x16x32_bf16 v[66:69], v[142:145], v[186:189], v[66:69]
	s_barrier
	s_add_u32 s2, s2, 0x40080
	s_addc_u32 s3, s3, 0
	s_add_i32 s12, s13, s35
	v_lshl_add_u64 v[130:131], s[2:3], 0, v[0:1]
	s_mov_b32 m0, s12
	s_nop 0
	global_load_lds_dwordx4 v[130:131], off
	v_lshl_add_u64 v[130:131], s[2:3], 0, v[154:155]
	s_add_i32 m0, s12, 0x2000
	s_nop 0
	global_load_lds_dwordx4 v[130:131], off
	s_waitcnt vmcnt(6)
	s_barrier
	v_mfma_f32_16x16x32_bf16 v[30:33], v[190:193], v[146:149], v[30:33]
	v_mfma_f32_16x16x32_bf16 v[26:29], v[198:201], v[146:149], v[26:29]
	v_mfma_f32_16x16x32_bf16 v[22:25], v[190:193], v[166:169], v[22:25]
	v_mfma_f32_16x16x32_bf16 v[18:21], v[198:201], v[166:169], v[18:21]
	v_mfma_f32_16x16x32_bf16 v[14:17], v[190:193], v[174:177], v[14:17]
	v_mfma_f32_16x16x32_bf16 v[10:13], v[198:201], v[174:177], v[10:13]
	v_mfma_f32_16x16x32_bf16 v[6:9], v[190:193], v[182:185], v[6:9]
	v_mfma_f32_16x16x32_bf16 v[2:5], v[198:201], v[182:185], v[2:5]
	v_mfma_f32_16x16x32_bf16 v[30:33], v[194:197], v[150:153], v[30:33]
	v_mfma_f32_16x16x32_bf16 v[26:29], v[234:237], v[150:153], v[26:29]
	v_mfma_f32_16x16x32_bf16 v[22:25], v[194:197], v[170:173], v[22:25]
	v_mfma_f32_16x16x32_bf16 v[18:21], v[234:237], v[170:173], v[18:21]
	s_add_i32 s47, s47, 2
	s_add_u32 s0, s0, 0x100
	s_addc_u32 s1, s1, 0
	s_add_u32 s45, s45, 0x100
	s_addc_u32 s46, s46, 0
	s_cmp_gt_u32 s47, 13
	v_mfma_f32_16x16x32_bf16 v[14:17], v[194:197], v[178:181], v[14:17]
	v_mfma_f32_16x16x32_bf16 v[10:13], v[234:237], v[178:181], v[10:13]
	v_mfma_f32_16x16x32_bf16 v[6:9], v[194:197], v[186:189], v[6:9]
	v_mfma_f32_16x16x32_bf16 v[2:5], v[234:237], v[186:189], v[2:5]
	s_barrier
	s_cbranch_scc0 .LBB0_366
